# row phases: wave sums via DPP scan + readlane instead of six dependent ds_bpermute round trips each
# speedup vs baseline: 1.0042x; 1.0042x over previous
.LBB0_207:
	v_lshl_add_u64 v[38:39], s[10:11], 0, v[34:35]
	v_lshl_add_u64 v[78:79], s[12:13], 0, v[34:35]
	global_load_dwordx4 v[46:49], v[38:39], off nt
	global_load_dwordx4 v[50:53], v[38:39], off offset:1024 nt
	global_load_dwordx4 v[54:57], v[38:39], off offset:3072 nt
	global_load_dwordx4 v[58:61], v[38:39], off offset:2048 nt
	global_load_dwordx4 v[62:65], v[78:79], off nt
	global_load_dwordx4 v[66:69], v[78:79], off offset:1024 nt
	global_load_dwordx4 v[70:73], v[78:79], off offset:3072 nt
	global_load_dwordx4 v[74:77], v[78:79], off offset:2048 nt
	v_lshl_add_u64 v[80:81], s[14:15], 0, v[16:17]
	v_add_co_u32_e32 v38, vcc, s20, v80
	v_lshl_add_u64 v[82:83], s[8:9], 0, v[16:17]
	s_nop 0
	v_addc_co_u32_e32 v39, vcc, 0, v81, vcc
	v_add_co_u32_e32 v78, vcc, s20, v82
	s_add_i32 s18, s18, 2
	s_nop 0
	v_addc_co_u32_e32 v79, vcc, 0, v83, vcc
	s_add_u32 s8, s8, 0x1000
	s_addc_u32 s9, s9, 0
	s_add_u32 s10, s10, 0x2000
	s_addc_u32 s11, s11, 0
	s_add_u32 s12, s12, 0x2000
	s_addc_u32 s13, s13, 0
	s_add_u32 s14, s14, 0x1000
	s_addc_u32 s15, s15, 0
	s_cmp_lt_i32 s18, s17
	s_waitcnt vmcnt(7)
	v_pk_mul_f32 v[80:81], v[48:49], v[48:49]
	v_pk_mul_f32 v[82:83], v[46:47], v[46:47]
	s_waitcnt vmcnt(6)
	v_pk_mul_f32 v[84:85], v[52:53], v[52:53]
	v_pk_mul_f32 v[86:87], v[50:51], v[50:51]
	s_waitcnt vmcnt(4)
	v_mul_f32_e32 v88, v59, v59
	v_mul_f32_e32 v90, v61, v61
	s_waitcnt vmcnt(3)
	v_pk_mul_f32 v[92:93], v[64:65], v[64:65]
	v_pk_mul_f32 v[94:95], v[62:63], v[62:63]
	s_waitcnt vmcnt(2)
	v_pk_mul_f32 v[96:97], v[68:69], v[68:69]
	v_pk_mul_f32 v[98:99], v[66:67], v[66:67]
	v_mul_f32_e32 v106, v56, v56
	v_mul_f32_e32 v107, v57, v57
	v_pk_mov_b32 v[104:105], v[82:83], v[80:81] op_sel:[1,0]
	v_mov_b32_e32 v83, v81
	v_pk_mov_b32 v[80:81], v[86:87], v[84:85] op_sel:[1,0]
	v_mov_b32_e32 v87, v85
	v_pk_fma_f32 v[84:85], v[58:59], v[58:59], v[88:89] op_sel_hi:[1,1,0]
	v_pk_fma_f32 v[88:89], v[60:61], v[60:61], v[90:91] op_sel_hi:[1,1,0]
	v_pk_mov_b32 v[90:91], v[94:95], v[92:93] op_sel:[1,0]
	v_mov_b32_e32 v95, v93
	v_pk_mov_b32 v[92:93], v[98:99], v[96:97] op_sel:[1,0]
	v_mov_b32_e32 v99, v97
	v_mul_f32_e32 v103, v55, v55
	s_waitcnt vmcnt(0)
	v_mul_f32_e32 v100, v75, v75
	v_mul_f32_e32 v102, v77, v77
	v_pk_add_f32 v[82:83], v[104:105], v[82:83]
	v_pk_add_f32 v[80:81], v[80:81], v[86:87]
	v_mov_b32_e32 v85, v106
	v_mov_b32_e32 v89, v107
	v_pk_add_f32 v[86:87], v[90:91], v[94:95]
	v_pk_add_f32 v[90:91], v[92:93], v[98:99]
	v_mul_f32_e32 v45, v54, v54
	v_mul_f32_e32 v108, v70, v70
	v_mul_f32_e32 v109, v71, v71
	v_mul_f32_e32 v110, v72, v72
	v_mul_f32_e32 v111, v73, v73
	v_pk_fma_f32 v[96:97], v[74:75], v[74:75], v[100:101] op_sel_hi:[1,1,0]
	v_pk_fma_f32 v[100:101], v[76:77], v[76:77], v[102:103] op_sel_hi:[1,1,0]
	v_pk_add_f32 v[82:83], v[82:83], v[82:83] op_sel:[0,1] op_sel_hi:[1,0]
	v_pk_add_f32 v[80:81], v[80:81], v[80:81] op_sel:[0,1] op_sel_hi:[1,0]
	v_pk_add_f32 v[84:85], v[84:85], v[88:89]
	v_pk_add_f32 v[86:87], v[86:87], v[86:87] op_sel:[0,1] op_sel_hi:[1,0]
	v_pk_add_f32 v[88:89], v[90:91], v[90:91] op_sel:[0,1] op_sel_hi:[1,0]
	v_mov_b32_e32 v97, v110
	v_mov_b32_e32 v101, v111
	v_mov_b32_e32 v83, v45
	v_mov_b32_e32 v81, v103
	v_mov_b32_e32 v87, v108
	v_mov_b32_e32 v89, v109
	v_pk_add_f32 v[90:91], v[96:97], v[100:101]
	v_pk_add_f32 v[80:81], v[82:83], v[80:81]
	v_pk_add_f32 v[82:83], v[86:87], v[88:89]
	v_pk_add_f32 v[80:81], v[80:81], v[84:85]
	v_pk_add_f32 v[82:83], v[82:83], v[90:91]
	v_mov_b32_e32 v85, v80
	v_mov_b32_e32 v84, v82
	v_mov_b32_e32 v80, v83
	v_pk_add_f32 v[80:81], v[84:85], v[80:81]
	s_nop 1
	v_add_f32_dpp v80, v80, v80 row_shr:1 row_mask:0xf bank_mask:0xf
	v_add_f32_dpp v81, v81, v81 row_shr:1 row_mask:0xf bank_mask:0xf
	s_nop 0
	v_add_f32_dpp v80, v80, v80 row_shr:2 row_mask:0xf bank_mask:0xf
	v_add_f32_dpp v81, v81, v81 row_shr:2 row_mask:0xf bank_mask:0xf
	s_nop 0
	v_add_f32_dpp v80, v80, v80 row_shr:4 row_mask:0xf bank_mask:0xf
	v_add_f32_dpp v81, v81, v81 row_shr:4 row_mask:0xf bank_mask:0xf
	s_nop 0
	v_add_f32_dpp v80, v80, v80 row_shr:8 row_mask:0xf bank_mask:0xf
	v_add_f32_dpp v81, v81, v81 row_shr:8 row_mask:0xf bank_mask:0xf
	s_nop 0
	v_add_f32_dpp v80, v80, v80 row_bcast:15 row_mask:0xa bank_mask:0xf
	v_add_f32_dpp v81, v81, v81 row_bcast:15 row_mask:0xa bank_mask:0xf
	s_nop 0
	v_add_f32_dpp v80, v80, v80 row_bcast:31 row_mask:0xc bank_mask:0xf
	v_add_f32_dpp v81, v81, v81 row_bcast:31 row_mask:0xc bank_mask:0xf
	s_nop 0
	s_nop 0
	v_readlane_b32 s98, v80, 63
	v_readlane_b32 s99, v81, 63
	v_mov_b32_e32 v80, s98
	v_mov_b32_e32 v81, s99
	s_nop 0
	v_pk_fma_f32 v[80:81], v[80:81], s[16:17], v[36:37] op_sel_hi:[1,0,0]
	s_nop 0
	v_mul_f32_e32 v45, 0x4b800000, v81
	v_cmp_gt_f32_e64 s[4:5], s19, v81
	v_mul_f32_e32 v82, 0x4b800000, v80
	v_cmp_gt_f32_e32 vcc, s19, v80
	v_cndmask_b32_e64 v45, v81, v45, s[4:5]
	v_rsq_f32_e32 v45, v45
	v_cndmask_b32_e32 v80, v80, v82, vcc
	v_rsq_f32_e32 v81, v80
	v_mul_f32_e32 v80, 0x45800000, v45
	v_cndmask_b32_e64 v80, v45, v80, s[4:5]
	v_mul_f32_e32 v82, 0x45800000, v81
	v_cndmask_b32_e32 v82, v81, v82, vcc
	v_pk_mul_f32 v[46:47], v[46:47], v[80:81] op_sel_hi:[1,0]
	v_pk_mul_f32 v[48:49], v[48:49], v[80:81] op_sel_hi:[1,0]
	v_pk_mul_f32 v[50:51], v[50:51], v[80:81] op_sel_hi:[1,0]
	v_pk_mul_f32 v[52:53], v[52:53], v[80:81] op_sel_hi:[1,0]
	v_pk_mul_f32 v[58:59], v[58:59], v[80:81] op_sel_hi:[1,0]
	v_pk_mul_f32 v[60:61], v[60:61], v[80:81] op_sel_hi:[1,0]
	v_pk_mul_f32 v[54:55], v[54:55], v[80:81] op_sel_hi:[1,0]
	v_pk_mul_f32 v[56:57], v[56:57], v[80:81] op_sel_hi:[1,0]
	v_pk_mul_f32 v[62:63], v[62:63], v[82:83] op_sel_hi:[1,0]
	v_pk_mul_f32 v[64:65], v[64:65], v[82:83] op_sel_hi:[1,0]
	v_pk_mul_f32 v[66:67], v[66:67], v[82:83] op_sel_hi:[1,0]
	v_pk_mul_f32 v[68:69], v[68:69], v[82:83] op_sel_hi:[1,0]
	v_pk_mul_f32 v[74:75], v[74:75], v[82:83] op_sel_hi:[1,0]
	v_pk_mul_f32 v[76:77], v[76:77], v[82:83] op_sel_hi:[1,0]
	v_pk_mul_f32 v[70:71], v[70:71], v[82:83] op_sel_hi:[1,0]
	v_pk_mul_f32 v[72:73], v[72:73], v[82:83] op_sel_hi:[1,0]
	v_pk_fma_f32 v[48:49], v[18:19], v[48:49], v[10:11]
	v_pk_fma_f32 v[46:47], v[20:21], v[46:47], v[8:9]
	v_pk_fma_f32 v[52:53], v[22:23], v[52:53], v[2:3]
	v_pk_fma_f32 v[50:51], v[24:25], v[50:51], v[0:1]
	v_pk_fma_f32 v[60:61], v[26:27], v[60:61], v[6:7]
	v_pk_fma_f32 v[58:59], v[28:29], v[58:59], v[4:5]
	v_pk_fma_f32 v[56:57], v[30:31], v[56:57], v[14:15]
	v_pk_fma_f32 v[54:55], v[32:33], v[54:55], v[12:13]
	v_pk_fma_f32 v[64:65], v[18:19], v[64:65], v[10:11]
	v_pk_fma_f32 v[62:63], v[20:21], v[62:63], v[8:9]
	v_pk_fma_f32 v[68:69], v[22:23], v[68:69], v[2:3]
	v_pk_fma_f32 v[66:67], v[24:25], v[66:67], v[0:1]
	v_pk_fma_f32 v[76:77], v[26:27], v[76:77], v[6:7]
	v_pk_fma_f32 v[74:75], v[28:29], v[74:75], v[4:5]
	v_pk_fma_f32 v[72:73], v[30:31], v[72:73], v[14:15]
	v_pk_fma_f32 v[70:71], v[32:33], v[70:71], v[12:13]
	v_cvt_pk_bf16_f32 v46, v46, v47
	v_cvt_pk_bf16_f32 v47, v48, v49
	v_cvt_pk_bf16_f32 v48, v50, v51
	v_cvt_pk_bf16_f32 v49, v52, v53
	v_cvt_pk_bf16_f32 v50, v58, v59
	v_cvt_pk_bf16_f32 v51, v60, v61
	v_cvt_pk_bf16_f32 v52, v54, v55
	v_cvt_pk_bf16_f32 v53, v56, v57
	v_cvt_pk_bf16_f32 v54, v62, v63
	v_cvt_pk_bf16_f32 v55, v64, v65
	v_cvt_pk_bf16_f32 v56, v66, v67
	v_cvt_pk_bf16_f32 v57, v68, v69
	v_cvt_pk_bf16_f32 v58, v74, v75
	v_cvt_pk_bf16_f32 v59, v76, v77
	v_cvt_pk_bf16_f32 v60, v70, v71
	v_cvt_pk_bf16_f32 v61, v72, v73
	global_store_dwordx2 v[38:39], v[46:47], off
	global_store_dwordx2 v[38:39], v[48:49], off offset:512
	global_store_dwordx2 v[38:39], v[50:51], off offset:1024
	global_store_dwordx2 v[38:39], v[52:53], off offset:1536
	global_store_dwordx2 v[78:79], v[54:55], off
	global_store_dwordx2 v[78:79], v[56:57], off offset:512
	global_store_dwordx2 v[78:79], v[58:59], off offset:1024
	global_store_dwordx2 v[78:79], v[60:61], off offset:1536
	s_cbranch_scc1 .LBB0_207

.LBB0_764:
	v_lshl_add_u64 v[74:75], s[8:9], 0, v[32:33]
	v_lshl_add_u64 v[72:73], s[10:11], 0, v[32:33]
	v_add_co_u32_e64 v104, s[4:5], s23, v74
	v_lshl_add_u64 v[16:17], s[18:19], 0, v[66:67]
	v_lshl_add_u64 v[76:77], s[14:15], 0, v[66:67]
	v_add_co_u32_e32 v102, vcc, 0x4000000, v72
	v_addc_co_u32_e64 v105, s[4:5], 0, v75, s[4:5]
	global_load_dwordx4 v[86:89], v[16:17], off nt
	global_load_dwordx4 v[90:93], v[16:17], off offset:1024 nt
	global_load_dwordx4 v[94:97], v[16:17], off offset:2048 nt
	global_load_dwordx4 v[98:101], v[16:17], off offset:3072 nt
	global_load_dwordx4 v[28:31], v[76:77], off nt
	global_load_dwordx4 v[24:27], v[76:77], off offset:1024 nt
	global_load_dwordx4 v[20:23], v[76:77], off offset:2048 nt
	s_nop 0
	global_load_dwordx4 v[16:19], v[76:77], off offset:3072 nt
	v_add_co_u32_e64 v76, s[4:5], s25, v72
	v_addc_co_u32_e32 v103, vcc, 0, v73, vcc
	s_nop 0
	v_addc_co_u32_e64 v77, s[4:5], 0, v73, s[4:5]
	global_load_dwordx2 v[106:107], v[104:105], off offset:1536 nt
	global_load_dwordx2 v[108:109], v[104:105], off nt
	global_load_dwordx2 v[110:111], v[104:105], off offset:512 nt
	global_load_dwordx2 v[112:113], v[104:105], off offset:1024 nt
	global_load_dwordx2 v[72:73], v[102:103], off offset:1536 nt
	s_nop 0
	global_load_dwordx2 v[104:105], v[102:103], off nt
	global_load_dwordx2 v[114:115], v[102:103], off offset:512 nt
	global_load_dwordx2 v[116:117], v[102:103], off offset:1024 nt
	v_lshl_add_u64 v[70:71], s[16:17], 0, v[32:33]
	v_add_co_u32_e64 v74, s[4:5], s25, v74
	v_lshl_add_u64 v[78:79], s[12:13], 0, v[32:33]
	s_nop 0
	v_addc_co_u32_e64 v75, s[4:5], 0, v75, s[4:5]
	s_add_i32 s22, s22, 2
	s_add_u32 s8, s8, 0x1000
	s_addc_u32 s9, s9, 0
	s_add_u32 s10, s10, 0x1000
	s_addc_u32 s11, s11, 0
	s_add_u32 s12, s12, 0x1000
	s_addc_u32 s13, s13, 0
	s_add_u32 s14, s14, 0x2000
	s_addc_u32 s15, s15, 0
	s_add_u32 s16, s16, 0x1000
	s_addc_u32 s17, s17, 0
	s_add_u32 s18, s18, 0x2000
	s_addc_u32 s19, s19, 0
	s_cmp_lt_i32 s22, s21
	s_waitcnt vmcnt(7)
	v_lshlrev_b32_e32 v103, 16, v106
	s_waitcnt vmcnt(6)
	v_lshlrev_b32_e32 v120, 16, v108
	v_and_b32_e32 v121, 0xffff0000, v108
	v_lshlrev_b32_e32 v108, 16, v109
	v_and_b32_e32 v109, 0xffff0000, v109
	s_waitcnt vmcnt(5)
	v_lshlrev_b32_e32 v123, 16, v111
	v_lshlrev_b32_e32 v122, 16, v110
	v_and_b32_e32 v111, 0xffff0000, v111
	v_and_b32_e32 v110, 0xffff0000, v110
	s_waitcnt vmcnt(2)
	v_lshlrev_b32_e32 v130, 16, v104
	v_and_b32_e32 v131, 0xffff0000, v104
	v_lshlrev_b32_e32 v104, 16, v105
	v_and_b32_e32 v105, 0xffff0000, v105
	s_waitcnt vmcnt(1)
	v_lshlrev_b32_e32 v133, 16, v115
	v_lshlrev_b32_e32 v132, 16, v114
	v_and_b32_e32 v115, 0xffff0000, v115
	v_and_b32_e32 v114, 0xffff0000, v114
	v_lshlrev_b32_e32 v124, 16, v112
	v_and_b32_e32 v125, 0xffff0000, v112
	v_lshlrev_b32_e32 v112, 16, v113
	v_and_b32_e32 v113, 0xffff0000, v113
	v_lshlrev_b32_e32 v127, 16, v72
	v_mul_f32_e32 v102, v109, v109
	v_pk_mul_f32 v[136:137], v[110:111], v[110:111]
	v_mul_f32_e32 v126, v121, v121
	v_mul_f32_e32 v144, v105, v105
	v_pk_mul_f32 v[146:147], v[114:115], v[114:115]
	v_mul_f32_e32 v148, v131, v131
	v_and_b32_e32 v119, 0xffff0000, v106
	v_lshlrev_b32_e32 v106, 16, v107
	s_waitcnt vmcnt(0)
	v_lshlrev_b32_e32 v134, 16, v116
	v_and_b32_e32 v135, 0xffff0000, v116
	v_lshlrev_b32_e32 v116, 16, v117
	v_and_b32_e32 v117, 0xffff0000, v117
	v_mov_b32_e32 v139, v103
	v_mul_f32_e32 v138, v125, v125
	v_mul_f32_e32 v140, v113, v113
	v_mov_b32_e32 v142, v122
	v_mov_b32_e32 v143, v110
	v_mov_b32_e32 v110, v123
	v_mov_b32_e32 v141, v127
	v_mov_b32_e32 v154, v132
	v_mov_b32_e32 v155, v114
	v_mov_b32_e32 v114, v133
	v_pk_fma_f32 v[156:157], v[108:109], v[108:109], v[102:103] op_sel_hi:[1,1,0]
	v_pk_fma_f32 v[122:123], v[122:123], v[122:123], v[136:137]
	v_pk_fma_f32 v[136:137], v[120:121], v[120:121], v[126:127] op_sel_hi:[1,1,0]
	v_pk_fma_f32 v[144:145], v[104:105], v[104:105], v[144:145] op_sel_hi:[1,1,0]
	v_pk_fma_f32 v[132:133], v[132:133], v[132:133], v[146:147]
	v_pk_fma_f32 v[146:147], v[130:131], v[130:131], v[148:149] op_sel_hi:[1,1,0]
	v_and_b32_e32 v129, 0xffff0000, v72
	v_lshlrev_b32_e32 v72, 16, v73
	v_and_b32_e32 v73, 0xffff0000, v73
	v_mul_f32_e32 v153, v106, v106
	v_mul_f32_e32 v150, v135, v135
	v_mul_f32_e32 v152, v117, v117
	v_pk_fma_f32 v[158:159], v[124:125], v[124:125], v[138:139] op_sel_hi:[1,1,0]
	v_pk_fma_f32 v[160:161], v[112:113], v[112:113], v[140:141] op_sel_hi:[1,1,0]
	v_mov_b32_e32 v102, v136
	v_mov_b32_e32 v138, v156
	v_mov_b32_e32 v126, v146
	v_mov_b32_e32 v140, v144
	v_and_b32_e32 v107, 0xffff0000, v107
	v_mul_f32_e32 v85, v119, v119
	v_mov_b32_e32 v118, v103
	v_mul_f32_e32 v163, v129, v129
	v_mul_f32_e32 v164, v72, v72
	v_mul_f32_e32 v165, v73, v73
	v_mov_b32_e32 v128, v127
	v_pk_fma_f32 v[148:149], v[134:135], v[134:135], v[150:151] op_sel_hi:[1,1,0]
	v_pk_fma_f32 v[150:151], v[116:117], v[116:117], v[152:153] op_sel_hi:[1,1,0]
	v_pk_add_f32 v[136:137], v[136:137], v[156:157]
	v_pk_add_f32 v[122:123], v[122:123], v[122:123] op_sel:[0,1] op_sel_hi:[1,0]
	v_pk_add_f32 v[144:145], v[146:147], v[144:145]
	v_pk_add_f32 v[132:133], v[132:133], v[132:133] op_sel:[0,1] op_sel_hi:[1,0]
	v_pk_mul_f32 v[102:103], v[102:103], v[138:139]
	v_pk_mul_f32 v[126:127], v[126:127], v[140:141]
	v_mul_f32_e32 v162, v107, v107
	v_mov_b32_e32 v149, v164
	v_mov_b32_e32 v151, v165
	v_mov_b32_e32 v123, v85
	v_mov_b32_e32 v133, v163
	v_mov_b32_e32 v137, v103
	v_mov_b32_e32 v145, v127
	v_mov_b32_e32 v159, v153
	v_mov_b32_e32 v161, v162
	v_pk_add_f32 v[140:141], v[148:149], v[150:151]
	v_pk_add_f32 v[102:103], v[136:137], v[122:123]
	v_pk_add_f32 v[122:123], v[144:145], v[132:133]
	v_pk_add_f32 v[138:139], v[158:159], v[160:161]
	v_pk_add_f32 v[122:123], v[122:123], v[140:141]
	v_pk_add_f32 v[102:103], v[102:103], v[138:139]
	v_add_f32_e32 v85, v122, v123
	v_mov_b32_e32 v126, v102
	s_nop 1
	v_add_f32_dpp v85, v85, v85 row_shr:1 row_mask:0xf bank_mask:0xf
	s_nop 1
	v_add_f32_dpp v85, v85, v85 row_shr:2 row_mask:0xf bank_mask:0xf
	s_nop 1
	v_add_f32_dpp v85, v85, v85 row_shr:4 row_mask:0xf bank_mask:0xf
	s_nop 1
	v_add_f32_dpp v85, v85, v85 row_shr:8 row_mask:0xf bank_mask:0xf
	s_nop 1
	v_add_f32_dpp v85, v85, v85 row_bcast:15 row_mask:0xa bank_mask:0xf
	s_nop 1
	v_add_f32_dpp v85, v85, v85 row_bcast:31 row_mask:0xc bank_mask:0xf
	s_nop 1
	v_readlane_b32 s98, v85, 63
	v_mov_b32_e32 v85, s98
	v_fmamk_f32 v85, v85, 0x3a800000, v68
	v_mul_f32_e32 v102, 0x4b800000, v85
	v_cmp_gt_f32_e32 vcc, s24, v85
	s_nop 1
	v_cndmask_b32_e32 v85, v85, v102, vcc
	v_rsq_f32_e32 v85, v85
	s_nop 0
	v_mul_f32_e32 v102, 0x45800000, v85
	v_cndmask_b32_e32 v102, v85, v102, vcc
	v_pk_mul_f32 v[122:123], v[102:103], v[130:131] op_sel_hi:[0,1]
	v_pk_mul_f32 v[104:105], v[102:103], v[104:105] op_sel_hi:[0,1]
	v_pk_mul_f32 v[130:131], v[102:103], v[154:155] op_sel_hi:[0,1]
	v_pk_mul_f32 v[114:115], v[102:103], v[114:115] op_sel_hi:[0,1]
	v_pk_mul_f32 v[132:133], v[102:103], v[134:135] op_sel_hi:[0,1]
	v_pk_mul_f32 v[116:117], v[102:103], v[116:117] op_sel_hi:[0,1]
	v_pk_mul_f32 v[128:129], v[102:103], v[128:129] op_sel_hi:[0,1]
	v_pk_mul_f32 v[72:73], v[102:103], v[72:73] op_sel_hi:[0,1]
	v_pk_fma_f32 v[88:89], v[34:35], v[104:105], v[88:89]
	v_pk_fma_f32 v[86:87], v[36:37], v[122:123], v[86:87]
	v_pk_fma_f32 v[92:93], v[38:39], v[114:115], v[92:93]
	v_pk_fma_f32 v[90:91], v[40:41], v[130:131], v[90:91]
	v_pk_fma_f32 v[96:97], v[42:43], v[116:117], v[96:97]
	v_pk_fma_f32 v[94:95], v[44:45], v[132:133], v[94:95]
	v_pk_fma_f32 v[72:73], v[46:47], v[72:73], v[100:101]
	v_pk_fma_f32 v[98:99], v[48:49], v[128:129], v[98:99]
	v_cvt_pk_bf16_f32 v86, v86, v87
	v_cvt_pk_bf16_f32 v87, v88, v89
	v_cvt_pk_bf16_f32 v88, v90, v91
	v_cvt_pk_bf16_f32 v89, v92, v93
	v_cvt_pk_bf16_f32 v90, v94, v95
	v_cvt_pk_bf16_f32 v91, v96, v97
	v_cvt_pk_bf16_f32 v92, v98, v99
	v_cvt_pk_bf16_f32 v93, v72, v73
	global_store_dwordx2 v[70:71], v[86:87], off nt
	global_store_dwordx2 v[70:71], v[88:89], off offset:512 nt
	global_store_dwordx2 v[70:71], v[90:91], off offset:1024 nt
	v_lshlrev_b32_e32 v95, 16, v87
	v_lshlrev_b32_e32 v94, 16, v86
	v_and_b32_e32 v87, 0xffff0000, v87
	v_and_b32_e32 v86, 0xffff0000, v86
	v_lshlrev_b32_e32 v97, 16, v89
	v_lshlrev_b32_e32 v96, 16, v88
	v_and_b32_e32 v89, 0xffff0000, v89
	v_and_b32_e32 v88, 0xffff0000, v88
	v_lshlrev_b32_e32 v72, 16, v90
	v_and_b32_e32 v73, 0xffff0000, v90
	global_store_dwordx2 v[70:71], v[92:93], off offset:1536 nt
	v_lshlrev_b32_e32 v70, 16, v92
	v_lshlrev_b32_e32 v90, 16, v91
	v_pk_mul_f32 v[98:99], v[86:87], v[86:87]
	v_pk_mul_f32 v[100:101], v[88:89], v[88:89]
	v_and_b32_e32 v91, 0xffff0000, v91
	v_mul_f32_e32 v71, v72, v72
	v_mul_f32_e32 v105, v73, v73
	v_mul_f32_e32 v102, v90, v90
	v_mov_b32_e32 v104, v70
	v_mov_b32_e32 v116, v94
	v_mov_b32_e32 v117, v86
	v_mov_b32_e32 v86, v95
	v_mov_b32_e32 v122, v96
	v_mov_b32_e32 v123, v88
	v_mov_b32_e32 v88, v97
	v_pk_fma_f32 v[94:95], v[94:95], v[94:95], v[98:99]
	v_pk_fma_f32 v[96:97], v[96:97], v[96:97], v[100:101]
	v_and_b32_e32 v85, 0xffff0000, v92
	v_lshlrev_b32_e32 v92, 16, v93
	v_and_b32_e32 v93, 0xffff0000, v93
	v_pk_fma_f32 v[98:99], v[90:91], v[90:91], v[102:103] op_sel_hi:[1,1,0]
	v_pk_add_f32 v[100:101], v[70:71], v[104:105]
	v_pk_add_f32 v[94:95], v[94:95], v[94:95] op_sel_hi:[0,1]
	v_pk_add_f32 v[96:97], v[96:97], v[96:97] op_sel_hi:[0,1]
	v_mul_f32_e32 v114, v70, v70
	v_mul_f32_e32 v98, v85, v85
	v_mov_b32_e32 v115, v101
	v_mul_f32_e32 v94, v92, v92
	v_mul_f32_e32 v96, v93, v93
	v_pk_add_f32 v[98:99], v[114:115], v[98:99]
	v_pk_add_f32 v[94:95], v[94:95], v[96:97]
	v_mov_b32_e32 v71, v85
	v_pk_add_f32 v[94:95], v[98:99], v[94:95]
	s_nop 0
	v_mov_b32_e32 v127, v94
	v_mov_b32_e32 v94, v103
	v_pk_add_f32 v[94:95], v[126:127], v[94:95]
	s_nop 1
	v_add_f32_dpp v94, v94, v94 row_shr:1 row_mask:0xf bank_mask:0xf
	v_add_f32_dpp v95, v95, v95 row_shr:1 row_mask:0xf bank_mask:0xf
	s_nop 0
	v_add_f32_dpp v94, v94, v94 row_shr:2 row_mask:0xf bank_mask:0xf
	v_add_f32_dpp v95, v95, v95 row_shr:2 row_mask:0xf bank_mask:0xf
	s_nop 0
	v_add_f32_dpp v94, v94, v94 row_shr:4 row_mask:0xf bank_mask:0xf
	v_add_f32_dpp v95, v95, v95 row_shr:4 row_mask:0xf bank_mask:0xf
	s_nop 0
	v_add_f32_dpp v94, v94, v94 row_shr:8 row_mask:0xf bank_mask:0xf
	v_add_f32_dpp v95, v95, v95 row_shr:8 row_mask:0xf bank_mask:0xf
	s_nop 0
	v_add_f32_dpp v94, v94, v94 row_bcast:15 row_mask:0xa bank_mask:0xf
	v_add_f32_dpp v95, v95, v95 row_bcast:15 row_mask:0xa bank_mask:0xf
	s_nop 0
	v_add_f32_dpp v94, v94, v94 row_bcast:31 row_mask:0xc bank_mask:0xf
	v_add_f32_dpp v95, v95, v95 row_bcast:31 row_mask:0xc bank_mask:0xf
	s_nop 0
	s_nop 0
	v_readlane_b32 s98, v94, 63
	v_readlane_b32 s99, v95, 63
	v_mov_b32_e32 v94, s98
	v_mov_b32_e32 v95, s99
	s_nop 0
	v_pk_fma_f32 v[94:95], v[94:95], s[20:21], v[68:69] op_sel_hi:[1,0,0]
	s_nop 0
	v_mul_f32_e32 v85, 0x4b800000, v95
	v_mul_f32_e32 v96, 0x4b800000, v94
	v_cmp_gt_f32_e32 vcc, s24, v94
	v_cmp_gt_f32_e64 s[4:5], s24, v95
	s_nop 0
	v_cndmask_b32_e32 v94, v94, v96, vcc
	v_cndmask_b32_e64 v85, v95, v85, s[4:5]
	v_rsq_f32_e32 v85, v85
	v_rsq_f32_e32 v95, v94
	v_mul_f32_e32 v94, 0x45800000, v85
	v_mul_f32_e32 v96, 0x45800000, v95
	v_cndmask_b32_e64 v94, v85, v94, s[4:5]
	v_cndmask_b32_e32 v96, v95, v96, vcc
	v_pk_mul_f32 v[98:99], v[94:95], v[116:117] op_sel_hi:[0,1]
	v_pk_mul_f32 v[86:87], v[94:95], v[86:87] op_sel_hi:[0,1]
	v_pk_mul_f32 v[100:101], v[94:95], v[122:123] op_sel_hi:[0,1]
	v_pk_mul_f32 v[88:89], v[94:95], v[88:89] op_sel_hi:[0,1]
	v_pk_mul_f32 v[72:73], v[94:95], v[72:73] op_sel_hi:[0,1]
	v_pk_mul_f32 v[90:91], v[94:95], v[90:91] op_sel_hi:[0,1]
	v_pk_mul_f32 v[70:71], v[94:95], v[70:71] op_sel_hi:[0,1]
	v_pk_mul_f32 v[92:93], v[94:95], v[92:93] op_sel_hi:[0,1]
	v_pk_mul_f32 v[94:95], v[96:97], v[120:121] op_sel_hi:[0,1]
	v_pk_mul_f32 v[102:103], v[96:97], v[108:109] op_sel_hi:[0,1]
	v_pk_mul_f32 v[104:105], v[96:97], v[142:143] op_sel_hi:[0,1]
	v_pk_mul_f32 v[108:109], v[96:97], v[110:111] op_sel_hi:[0,1]
	v_pk_mul_f32 v[110:111], v[96:97], v[124:125] op_sel_hi:[0,1]
	v_pk_mul_f32 v[112:113], v[96:97], v[112:113] op_sel_hi:[0,1]
	v_pk_mul_f32 v[114:115], v[96:97], v[118:119] op_sel_hi:[0,1]
	v_pk_fma_f32 v[86:87], v[50:51], v[86:87], v[2:3]
	v_pk_fma_f32 v[98:99], v[52:53], v[98:99], v[0:1]
	v_pk_fma_f32 v[30:31], v[34:35], v[102:103], v[30:31]
	v_pk_fma_f32 v[28:29], v[36:37], v[94:95], v[28:29]
	v_pk_fma_f32 v[26:27], v[38:39], v[108:109], v[26:27]
	v_pk_fma_f32 v[24:25], v[40:41], v[104:105], v[24:25]
	v_pk_mul_f32 v[96:97], v[96:97], v[106:107] op_sel_hi:[0,1]
	v_pk_fma_f32 v[88:89], v[54:55], v[88:89], v[6:7]
	v_pk_fma_f32 v[100:101], v[56:57], v[100:101], v[4:5]
	v_pk_fma_f32 v[90:91], v[58:59], v[90:91], v[10:11]
	v_pk_fma_f32 v[72:73], v[60:61], v[72:73], v[8:9]
	v_pk_fma_f32 v[92:93], v[62:63], v[92:93], v[14:15]
	v_pk_fma_f32 v[70:71], v[64:65], v[70:71], v[12:13]
	v_pk_fma_f32 v[22:23], v[42:43], v[112:113], v[22:23]
	v_pk_fma_f32 v[20:21], v[44:45], v[110:111], v[20:21]
	v_pk_fma_f32 v[16:17], v[48:49], v[114:115], v[16:17]
	v_cvt_pk_bf16_f32 v94, v98, v99
	v_cvt_pk_bf16_f32 v95, v86, v87
	v_cvt_pk_bf16_f32 v28, v28, v29
	v_cvt_pk_bf16_f32 v29, v30, v31
	v_cvt_pk_bf16_f32 v24, v24, v25
	v_cvt_pk_bf16_f32 v25, v26, v27
	v_pk_fma_f32 v[18:19], v[46:47], v[96:97], v[18:19]
	v_cvt_pk_bf16_f32 v86, v100, v101
	v_cvt_pk_bf16_f32 v87, v88, v89
	v_cvt_pk_bf16_f32 v72, v72, v73
	v_cvt_pk_bf16_f32 v73, v90, v91
	v_cvt_pk_bf16_f32 v70, v70, v71
	v_cvt_pk_bf16_f32 v71, v92, v93
	v_cvt_pk_bf16_f32 v20, v20, v21
	v_cvt_pk_bf16_f32 v21, v22, v23
	v_cvt_pk_bf16_f32 v16, v16, v17
	global_store_dwordx2 v[76:77], v[94:95], off
	global_store_dwordx2 v[76:77], v[86:87], off offset:512
	global_store_dwordx2 v[76:77], v[72:73], off offset:1024
	global_store_dwordx2 v[76:77], v[70:71], off offset:1536
	global_store_dwordx2 v[78:79], v[28:29], off nt
	global_store_dwordx2 v[78:79], v[24:25], off offset:512 nt
	global_store_dwordx2 v[78:79], v[20:21], off offset:1024 nt
	v_lshlrev_b32_e32 v23, 16, v29
	v_lshlrev_b32_e32 v22, 16, v28
	v_and_b32_e32 v27, 0xffff0000, v29
	v_and_b32_e32 v26, 0xffff0000, v28
	v_lshlrev_b32_e32 v29, 16, v25
	v_lshlrev_b32_e32 v28, 16, v24
	v_and_b32_e32 v25, 0xffff0000, v25
	v_and_b32_e32 v24, 0xffff0000, v24
	v_cvt_pk_bf16_f32 v17, v18, v19
	v_lshlrev_b32_e32 v18, 16, v20
	v_and_b32_e32 v19, 0xffff0000, v20
	v_lshlrev_b32_e32 v20, 16, v16
	v_lshlrev_b32_e32 v30, 16, v21
	v_pk_mul_f32 v[70:71], v[26:27], v[26:27]
	v_pk_mul_f32 v[72:73], v[24:25], v[24:25]
	global_store_dwordx2 v[78:79], v[16:17], off offset:1536 nt
	v_and_b32_e32 v79, 0xffff0000, v16
	v_and_b32_e32 v31, 0xffff0000, v21
	v_mul_f32_e32 v21, v18, v18
	v_mul_f32_e32 v77, v19, v19
	v_mul_f32_e32 v78, v30, v30
	v_mov_b32_e32 v76, v20
	v_mov_b32_e32 v88, v22
	v_mov_b32_e32 v89, v26
	v_mov_b32_e32 v26, v23
	v_mov_b32_e32 v90, v28
	v_mov_b32_e32 v91, v24
	v_mov_b32_e32 v24, v29
	v_pk_fma_f32 v[22:23], v[22:23], v[22:23], v[70:71]
	v_pk_fma_f32 v[28:29], v[28:29], v[28:29], v[72:73]
	v_lshlrev_b32_e32 v16, 16, v17
	v_and_b32_e32 v17, 0xffff0000, v17
	v_pk_fma_f32 v[70:71], v[30:31], v[30:31], v[78:79] op_sel_hi:[1,1,0]
	v_pk_add_f32 v[72:73], v[20:21], v[76:77]
	v_pk_add_f32 v[22:23], v[22:23], v[22:23] op_sel_hi:[0,1]
	v_pk_add_f32 v[28:29], v[28:29], v[28:29] op_sel_hi:[0,1]
	v_mul_f32_e32 v86, v20, v20
	v_mul_f32_e32 v70, v79, v79
	v_mov_b32_e32 v87, v73
	v_mul_f32_e32 v22, v16, v16
	v_mul_f32_e32 v28, v17, v17
	v_pk_add_f32 v[70:71], v[86:87], v[70:71]
	v_pk_add_f32 v[22:23], v[22:23], v[28:29]
	v_mov_b32_e32 v21, v79
	v_pk_add_f32 v[22:23], v[70:71], v[22:23]
	s_nop 0
	v_add_f32_e32 v22, v22, v23
	s_nop 1
	v_add_f32_dpp v22, v22, v22 row_shr:1 row_mask:0xf bank_mask:0xf
	s_nop 1
	v_add_f32_dpp v22, v22, v22 row_shr:2 row_mask:0xf bank_mask:0xf
	s_nop 1
	v_add_f32_dpp v22, v22, v22 row_shr:4 row_mask:0xf bank_mask:0xf
	s_nop 1
	v_add_f32_dpp v22, v22, v22 row_shr:8 row_mask:0xf bank_mask:0xf
	s_nop 1
	v_add_f32_dpp v22, v22, v22 row_bcast:15 row_mask:0xa bank_mask:0xf
	s_nop 1
	v_add_f32_dpp v22, v22, v22 row_bcast:31 row_mask:0xc bank_mask:0xf
	s_nop 1
	v_readlane_b32 s98, v22, 63
	v_mov_b32_e32 v22, s98
	v_fmamk_f32 v22, v22, 0x3a800000, v68
	v_mul_f32_e32 v23, 0x4b800000, v22
	v_cmp_gt_f32_e32 vcc, s24, v22
	s_nop 1
	v_cndmask_b32_e32 v22, v22, v23, vcc
	v_rsq_f32_e32 v22, v22
	s_nop 0
	v_mul_f32_e32 v23, 0x45800000, v22
	v_cndmask_b32_e32 v22, v22, v23, vcc
	v_pk_mul_f32 v[28:29], v[22:23], v[88:89] op_sel_hi:[0,1]
	v_pk_mul_f32 v[26:27], v[22:23], v[26:27] op_sel_hi:[0,1]
	v_pk_mul_f32 v[70:71], v[22:23], v[90:91] op_sel_hi:[0,1]
	v_pk_mul_f32 v[24:25], v[22:23], v[24:25] op_sel_hi:[0,1]
	v_pk_mul_f32 v[18:19], v[22:23], v[18:19] op_sel_hi:[0,1]
	v_pk_mul_f32 v[30:31], v[22:23], v[30:31] op_sel_hi:[0,1]
	v_pk_mul_f32 v[20:21], v[22:23], v[20:21] op_sel_hi:[0,1]
	v_pk_mul_f32 v[16:17], v[22:23], v[16:17] op_sel_hi:[0,1]
	v_pk_fma_f32 v[22:23], v[50:51], v[26:27], v[2:3]
	v_pk_fma_f32 v[26:27], v[52:53], v[28:29], v[0:1]
	v_pk_fma_f32 v[24:25], v[54:55], v[24:25], v[6:7]
	v_pk_fma_f32 v[28:29], v[56:57], v[70:71], v[4:5]
	v_pk_fma_f32 v[30:31], v[58:59], v[30:31], v[10:11]
	v_pk_fma_f32 v[18:19], v[60:61], v[18:19], v[8:9]
	v_pk_fma_f32 v[16:17], v[62:63], v[16:17], v[14:15]
	v_pk_fma_f32 v[20:21], v[64:65], v[20:21], v[12:13]
	v_cvt_pk_bf16_f32 v26, v26, v27
	v_cvt_pk_bf16_f32 v27, v22, v23
	v_cvt_pk_bf16_f32 v22, v28, v29
	v_cvt_pk_bf16_f32 v23, v24, v25
	v_cvt_pk_bf16_f32 v18, v18, v19
	v_cvt_pk_bf16_f32 v19, v30, v31
	v_cvt_pk_bf16_f32 v20, v20, v21
	v_cvt_pk_bf16_f32 v21, v16, v17
	global_store_dwordx2 v[74:75], v[26:27], off
	global_store_dwordx2 v[74:75], v[22:23], off offset:512
	global_store_dwordx2 v[74:75], v[18:19], off offset:1024
	global_store_dwordx2 v[74:75], v[20:21], off offset:1536
	s_cbranch_scc1 .LBB0_764

.LBB0_980:
	v_lshl_add_u64 v[94:95], s[8:9], 0, v[32:33]
	v_add_co_u32_e64 v98, s[4:5], s19, v94
	s_add_i32 s14, s13, s17
	s_nop 0
	v_addc_co_u32_e64 v99, s[4:5], 0, v95, s[4:5]
	v_add_co_u32_e32 v96, vcc, 0x4000000, v94
	v_add_co_u32_e64 v100, s[4:5], s20, v94
	v_lshl_add_u64 v[92:93], s[10:11], 0, v[32:33]
	s_ashr_i32 s15, s14, 31
	v_addc_co_u32_e64 v101, s[4:5], 0, v95, s[4:5]
	v_addc_co_u32_e32 v97, vcc, 0, v95, vcc
	global_load_dwordx2 v[110:111], v[92:93], off nt
	global_load_dwordx2 v[112:113], v[92:93], off offset:512 nt
	global_load_dwordx2 v[114:115], v[92:93], off offset:1024 nt
	global_load_dwordx2 v[116:117], v[92:93], off offset:1536 nt
	s_lshl_b64 s[4:5], s[14:15], 11
	global_load_dwordx2 v[118:119], v[96:97], off offset:1536 nt
	global_load_dwordx2 v[120:121], v[96:97], off nt
	global_load_dwordx2 v[122:123], v[96:97], off offset:512 nt
	global_load_dwordx2 v[124:125], v[96:97], off offset:1024 nt
	v_lshl_add_u64 v[126:127], v[84:85], 0, s[4:5]
	v_lshl_add_u64 v[102:103], v[82:83], 0, s[4:5]
	global_load_dwordx2 v[128:129], v[102:103], off nt
	global_load_dwordx2 v[130:131], v[102:103], off offset:512 nt
	global_load_dwordx2 v[132:133], v[102:103], off offset:1024 nt
	global_load_dwordx2 v[134:135], v[102:103], off offset:1536 nt
	global_load_dwordx2 v[136:137], v[126:127], off offset:1536 nt
	global_load_dwordx2 v[138:139], v[126:127], off nt
	global_load_dwordx2 v[140:141], v[126:127], off offset:512 nt
	s_nop 0
	global_load_dwordx2 v[126:127], v[126:127], off offset:1024 nt
	v_lshl_add_u64 v[94:95], v[86:87], 0, s[4:5]
	v_lshl_add_u64 v[96:97], v[88:89], 0, s[4:5]
	s_add_i32 s17, s17, 2
	s_add_u32 s8, s8, 0x1000
	s_addc_u32 s9, s9, 0
	s_add_u32 s10, s10, 0x1000
	s_addc_u32 s11, s11, 0
	s_cmp_lt_i32 s17, s16
	s_waitcnt vmcnt(15)
	v_lshlrev_b32_e32 v142, 16, v110
	v_and_b32_e32 v143, 0xffff0000, v110
	s_waitcnt vmcnt(11)
	v_lshlrev_b32_e32 v151, 16, v118
	s_waitcnt vmcnt(10)
	v_lshlrev_b32_e32 v154, 16, v120
	v_and_b32_e32 v155, 0xffff0000, v120
	v_lshlrev_b32_e32 v120, 16, v121
	v_and_b32_e32 v121, 0xffff0000, v121
	s_waitcnt vmcnt(9)
	v_lshlrev_b32_e32 v157, 16, v123
	v_lshlrev_b32_e32 v156, 16, v122
	v_and_b32_e32 v123, 0xffff0000, v123
	v_and_b32_e32 v122, 0xffff0000, v122
	s_waitcnt vmcnt(8)
	v_lshlrev_b32_e32 v158, 16, v124
	v_and_b32_e32 v159, 0xffff0000, v124
	v_lshlrev_b32_e32 v124, 16, v125
	v_and_b32_e32 v125, 0xffff0000, v125
	s_waitcnt vmcnt(3)
	v_lshlrev_b32_e32 v169, 16, v136
	v_mul_f32_e32 v150, v121, v121
	v_pk_mul_f32 v[172:173], v[122:123], v[122:123]
	v_mul_f32_e32 v168, v155, v155
	v_mov_b32_e32 v175, v151
	v_mul_f32_e32 v174, v125, v125
	v_mov_b32_e32 v176, v156
	v_mov_b32_e32 v177, v122
	v_mov_b32_e32 v122, v157
	s_waitcnt vmcnt(2)
	v_lshlrev_b32_e32 v178, 16, v138
	v_and_b32_e32 v179, 0xffff0000, v138
	v_lshlrev_b32_e32 v138, 16, v139
	v_and_b32_e32 v139, 0xffff0000, v139
	s_waitcnt vmcnt(1)
	v_lshlrev_b32_e32 v181, 16, v141
	v_lshlrev_b32_e32 v180, 16, v140
	v_and_b32_e32 v141, 0xffff0000, v141
	v_and_b32_e32 v140, 0xffff0000, v140
	v_pk_fma_f32 v[184:185], v[120:121], v[120:121], v[150:151] op_sel_hi:[1,1,0]
	v_pk_fma_f32 v[156:157], v[156:157], v[156:157], v[172:173]
	v_pk_fma_f32 v[172:173], v[154:155], v[154:155], v[168:169] op_sel_hi:[1,1,0]
	v_and_b32_e32 v153, 0xffff0000, v118
	v_lshlrev_b32_e32 v118, 16, v119
	v_and_b32_e32 v119, 0xffff0000, v119
	v_and_b32_e32 v171, 0xffff0000, v136
	v_mul_f32_e32 v170, v159, v159
	v_pk_fma_f32 v[188:189], v[124:125], v[124:125], v[174:175] op_sel_hi:[1,1,0]
	v_mul_f32_e32 v168, v139, v139
	v_pk_mul_f32 v[192:193], v[140:141], v[140:141]
	v_mul_f32_e32 v194, v179, v179
	v_mov_b32_e32 v195, v169
	v_mov_b32_e32 v150, v172
	v_mov_b32_e32 v174, v184
	v_mul_f32_e32 v109, v153, v153
	v_mul_f32_e32 v191, v118, v118
	v_mul_f32_e32 v197, v119, v119
	v_mov_b32_e32 v152, v151
	s_waitcnt vmcnt(0)
	v_lshlrev_b32_e32 v182, 16, v126
	v_and_b32_e32 v183, 0xffff0000, v126
	v_lshlrev_b32_e32 v126, 16, v127
	v_and_b32_e32 v127, 0xffff0000, v127
	v_pk_fma_f32 v[186:187], v[158:159], v[158:159], v[170:171] op_sel_hi:[1,1,0]
	v_mov_b32_e32 v200, v180
	v_mov_b32_e32 v201, v140
	v_mov_b32_e32 v140, v181
	v_pk_add_f32 v[172:173], v[172:173], v[184:185]
	v_pk_add_f32 v[156:157], v[156:157], v[156:157] op_sel:[0,1] op_sel_hi:[1,0]
	v_pk_fma_f32 v[184:185], v[138:139], v[138:139], v[168:169] op_sel_hi:[1,1,0]
	v_pk_fma_f32 v[180:181], v[180:181], v[180:181], v[192:193]
	v_pk_fma_f32 v[192:193], v[178:179], v[178:179], v[194:195] op_sel_hi:[1,1,0]
	v_pk_mul_f32 v[150:151], v[150:151], v[174:175]
	v_lshlrev_b32_e32 v136, 16, v137
	v_and_b32_e32 v137, 0xffff0000, v137
	v_mul_f32_e32 v196, v183, v183
	v_mul_f32_e32 v198, v127, v127
	v_mov_b32_e32 v187, v191
	v_mov_b32_e32 v189, v197
	v_mov_b32_e32 v157, v109
	v_mov_b32_e32 v168, v192
	v_mov_b32_e32 v194, v184
	v_mov_b32_e32 v173, v151
	v_mul_f32_e32 v202, v171, v171
	v_mul_f32_e32 v203, v136, v136
	v_mul_f32_e32 v204, v137, v137
	v_pk_fma_f32 v[196:197], v[182:183], v[182:183], v[196:197] op_sel_hi:[1,1,0]
	v_pk_fma_f32 v[198:199], v[126:127], v[126:127], v[198:199] op_sel_hi:[1,1,0]
	v_pk_add_f32 v[174:175], v[186:187], v[188:189]
	v_pk_add_f32 v[184:185], v[192:193], v[184:185]
	v_pk_add_f32 v[180:181], v[180:181], v[180:181] op_sel:[0,1] op_sel_hi:[1,0]
	v_pk_mul_f32 v[150:151], v[168:169], v[194:195]
	v_pk_add_f32 v[156:157], v[172:173], v[156:157]
	v_mov_b32_e32 v197, v203
	v_mov_b32_e32 v199, v204
	v_mov_b32_e32 v181, v202
	v_mov_b32_e32 v185, v151
	v_pk_add_f32 v[150:151], v[156:157], v[174:175]
	v_mov_b32_e32 v170, v169
	v_pk_add_f32 v[168:169], v[196:197], v[198:199]
	v_pk_add_f32 v[156:157], v[184:185], v[180:181]
	v_add_f32_e32 v109, v150, v151
	v_pk_add_f32 v[150:151], v[156:157], v[168:169]
	v_mov_b32_e32 v156, v150
	v_lshlrev_b32_e32 v110, 16, v111
	v_and_b32_e32 v111, 0xffff0000, v111
	v_lshlrev_b32_e32 v144, 16, v112
	v_and_b32_e32 v145, 0xffff0000, v112
	v_lshlrev_b32_e32 v112, 16, v113
	v_and_b32_e32 v113, 0xffff0000, v113
	v_lshlrev_b32_e32 v146, 16, v114
	v_and_b32_e32 v147, 0xffff0000, v114
	v_lshlrev_b32_e32 v114, 16, v115
	v_and_b32_e32 v115, 0xffff0000, v115
	v_lshlrev_b32_e32 v148, 16, v116
	v_and_b32_e32 v149, 0xffff0000, v116
	v_lshlrev_b32_e32 v116, 16, v117
	v_and_b32_e32 v117, 0xffff0000, v117
	v_lshlrev_b32_e32 v160, 16, v128
	v_and_b32_e32 v161, 0xffff0000, v128
	v_lshlrev_b32_e32 v128, 16, v129
	v_and_b32_e32 v129, 0xffff0000, v129
	v_lshlrev_b32_e32 v162, 16, v130
	v_and_b32_e32 v163, 0xffff0000, v130
	v_lshlrev_b32_e32 v130, 16, v131
	v_and_b32_e32 v131, 0xffff0000, v131
	v_lshlrev_b32_e32 v164, 16, v132
	s_nop 1
	v_add_f32_dpp v109, v109, v109 row_shr:1 row_mask:0xf bank_mask:0xf
	s_nop 1
	v_add_f32_dpp v109, v109, v109 row_shr:2 row_mask:0xf bank_mask:0xf
	s_nop 1
	v_add_f32_dpp v109, v109, v109 row_shr:4 row_mask:0xf bank_mask:0xf
	s_nop 1
	v_add_f32_dpp v109, v109, v109 row_shr:8 row_mask:0xf bank_mask:0xf
	s_nop 1
	v_add_f32_dpp v109, v109, v109 row_bcast:15 row_mask:0xa bank_mask:0xf
	s_nop 1
	v_add_f32_dpp v109, v109, v109 row_bcast:31 row_mask:0xc bank_mask:0xf
	s_nop 1
	v_readlane_b32 s98, v109, 63
	v_mov_b32_e32 v109, s98
	v_fmamk_f32 v109, v109, 0x3a800000, v90
	v_mul_f32_e32 v150, 0x4b800000, v109
	v_cmp_gt_f32_e32 vcc, s18, v109
	v_and_b32_e32 v165, 0xffff0000, v132
	v_lshlrev_b32_e32 v132, 16, v133
	v_cndmask_b32_e32 v109, v109, v150, vcc
	v_rsq_f32_e32 v109, v109
	v_and_b32_e32 v133, 0xffff0000, v133
	v_lshlrev_b32_e32 v166, 16, v134
	v_and_b32_e32 v167, 0xffff0000, v134
	v_mul_f32_e32 v150, 0x45800000, v109
	v_cndmask_b32_e32 v150, v109, v150, vcc
	v_pk_mul_f32 v[154:155], v[150:151], v[154:155] op_sel_hi:[0,1]
	v_pk_mul_f32 v[120:121], v[150:151], v[120:121] op_sel_hi:[0,1]
	v_pk_mul_f32 v[168:169], v[150:151], v[176:177] op_sel_hi:[0,1]
	v_pk_mul_f32 v[122:123], v[150:151], v[122:123] op_sel_hi:[0,1]
	v_pk_mul_f32 v[158:159], v[150:151], v[158:159] op_sel_hi:[0,1]
	v_pk_mul_f32 v[124:125], v[150:151], v[124:125] op_sel_hi:[0,1]
	v_pk_mul_f32 v[152:153], v[150:151], v[152:153] op_sel_hi:[0,1]
	v_pk_mul_f32 v[118:119], v[150:151], v[118:119] op_sel_hi:[0,1]
	v_pk_fma_f32 v[110:111], v[38:39], v[120:121], v[110:111]
	v_pk_fma_f32 v[120:121], v[40:41], v[154:155], v[142:143]
	v_pk_fma_f32 v[112:113], v[46:47], v[122:123], v[112:113]
	v_pk_fma_f32 v[122:123], v[48:49], v[168:169], v[144:145]
	v_pk_fma_f32 v[114:115], v[58:59], v[124:125], v[114:115]
	v_pk_fma_f32 v[124:125], v[60:61], v[158:159], v[146:147]
	v_pk_fma_f32 v[116:117], v[70:71], v[118:119], v[116:117]
	v_pk_fma_f32 v[118:119], v[72:73], v[152:153], v[148:149]
	v_cvt_pk_bf16_f32 v120, v120, v121
	v_cvt_pk_bf16_f32 v121, v110, v111
	v_cvt_pk_bf16_f32 v110, v122, v123
	v_cvt_pk_bf16_f32 v111, v112, v113
	v_cvt_pk_bf16_f32 v112, v124, v125
	v_cvt_pk_bf16_f32 v113, v114, v115
	v_cvt_pk_bf16_f32 v114, v118, v119
	v_cvt_pk_bf16_f32 v115, v116, v117
	global_store_dwordx2 v[92:93], v[120:121], off nt
	global_store_dwordx2 v[92:93], v[110:111], off offset:512 nt
	global_store_dwordx2 v[92:93], v[112:113], off offset:1024 nt
	v_lshlrev_b32_e32 v119, 16, v121
	v_lshlrev_b32_e32 v118, 16, v120
	v_and_b32_e32 v121, 0xffff0000, v121
	v_and_b32_e32 v120, 0xffff0000, v120
	v_lshlrev_b32_e32 v123, 16, v111
	v_lshlrev_b32_e32 v122, 16, v110
	v_and_b32_e32 v111, 0xffff0000, v111
	v_and_b32_e32 v110, 0xffff0000, v110
	v_lshlrev_b32_e32 v116, 16, v112
	v_and_b32_e32 v117, 0xffff0000, v112
	global_store_dwordx2 v[92:93], v[114:115], off offset:1536 nt
	v_lshlrev_b32_e32 v92, 16, v114
	v_lshlrev_b32_e32 v112, 16, v113
	v_pk_mul_f32 v[124:125], v[120:121], v[120:121]
	v_pk_mul_f32 v[142:143], v[110:111], v[110:111]
	v_and_b32_e32 v113, 0xffff0000, v113
	v_mul_f32_e32 v93, v116, v116
	v_mul_f32_e32 v145, v117, v117
	v_mul_f32_e32 v146, v112, v112
	v_mov_b32_e32 v144, v92
	v_mov_b32_e32 v152, v118
	v_mov_b32_e32 v153, v120
	v_mov_b32_e32 v120, v119
	v_mov_b32_e32 v154, v122
	v_mov_b32_e32 v155, v110
	v_mov_b32_e32 v110, v123
	v_pk_fma_f32 v[118:119], v[118:119], v[118:119], v[124:125]
	v_pk_fma_f32 v[122:123], v[122:123], v[122:123], v[142:143]
	v_and_b32_e32 v109, 0xffff0000, v114
	v_lshlrev_b32_e32 v114, 16, v115
	v_and_b32_e32 v115, 0xffff0000, v115
	v_pk_fma_f32 v[124:125], v[112:113], v[112:113], v[146:147] op_sel_hi:[1,1,0]
	v_pk_add_f32 v[142:143], v[92:93], v[144:145]
	v_pk_add_f32 v[118:119], v[118:119], v[118:119] op_sel_hi:[0,1]
	v_pk_add_f32 v[122:123], v[122:123], v[122:123] op_sel_hi:[0,1]
	v_mul_f32_e32 v148, v92, v92
	v_mul_f32_e32 v124, v109, v109
	v_mov_b32_e32 v149, v143
	v_mul_f32_e32 v118, v114, v114
	v_mul_f32_e32 v122, v115, v115
	v_pk_add_f32 v[124:125], v[148:149], v[124:125]
	v_pk_add_f32 v[118:119], v[118:119], v[122:123]
	v_mov_b32_e32 v93, v109
	v_pk_add_f32 v[118:119], v[124:125], v[118:119]
	v_lshlrev_b32_e32 v134, 16, v135
	v_mov_b32_e32 v157, v118
	v_mov_b32_e32 v118, v151
	v_pk_add_f32 v[118:119], v[156:157], v[118:119]
	v_and_b32_e32 v135, 0xffff0000, v135
	s_nop 1
	v_add_f32_dpp v118, v118, v118 row_shr:1 row_mask:0xf bank_mask:0xf
	v_add_f32_dpp v119, v119, v119 row_shr:1 row_mask:0xf bank_mask:0xf
	s_nop 0
	v_add_f32_dpp v118, v118, v118 row_shr:2 row_mask:0xf bank_mask:0xf
	v_add_f32_dpp v119, v119, v119 row_shr:2 row_mask:0xf bank_mask:0xf
	s_nop 0
	v_add_f32_dpp v118, v118, v118 row_shr:4 row_mask:0xf bank_mask:0xf
	v_add_f32_dpp v119, v119, v119 row_shr:4 row_mask:0xf bank_mask:0xf
	s_nop 0
	v_add_f32_dpp v118, v118, v118 row_shr:8 row_mask:0xf bank_mask:0xf
	v_add_f32_dpp v119, v119, v119 row_shr:8 row_mask:0xf bank_mask:0xf
	s_nop 0
	v_add_f32_dpp v118, v118, v118 row_bcast:15 row_mask:0xa bank_mask:0xf
	v_add_f32_dpp v119, v119, v119 row_bcast:15 row_mask:0xa bank_mask:0xf
	s_nop 0
	v_add_f32_dpp v118, v118, v118 row_bcast:31 row_mask:0xc bank_mask:0xf
	v_add_f32_dpp v119, v119, v119 row_bcast:31 row_mask:0xc bank_mask:0xf
	s_nop 0
	s_nop 0
	v_readlane_b32 s98, v118, 63
	v_readlane_b32 s99, v119, 63
	v_mov_b32_e32 v118, s98
	v_mov_b32_e32 v119, s99
	s_nop 0
	v_pk_fma_f32 v[118:119], v[118:119], s[12:13], v[90:91] op_sel_hi:[1,0,0]
	s_nop 0
	v_mul_f32_e32 v109, 0x4b800000, v119
	v_mul_f32_e32 v122, 0x4b800000, v118
	v_cmp_gt_f32_e32 vcc, s18, v118
	v_cmp_gt_f32_e64 s[4:5], s18, v119
	s_nop 0
	v_cndmask_b32_e32 v118, v118, v122, vcc
	v_cndmask_b32_e64 v109, v119, v109, s[4:5]
	v_rsq_f32_e32 v109, v109
	v_rsq_f32_e32 v119, v118
	v_mul_f32_e32 v118, 0x45800000, v109
	v_mul_f32_e32 v122, 0x45800000, v119
	v_cndmask_b32_e64 v118, v109, v118, s[4:5]
	v_cndmask_b32_e32 v122, v119, v122, vcc
	v_pk_mul_f32 v[124:125], v[118:119], v[152:153] op_sel_hi:[0,1]
	v_pk_mul_f32 v[120:121], v[118:119], v[120:121] op_sel_hi:[0,1]
	v_pk_mul_f32 v[142:143], v[118:119], v[154:155] op_sel_hi:[0,1]
	v_pk_mul_f32 v[110:111], v[118:119], v[110:111] op_sel_hi:[0,1]
	v_pk_mul_f32 v[116:117], v[118:119], v[116:117] op_sel_hi:[0,1]
	v_pk_mul_f32 v[112:113], v[118:119], v[112:113] op_sel_hi:[0,1]
	v_pk_mul_f32 v[92:93], v[118:119], v[92:93] op_sel_hi:[0,1]
	v_pk_mul_f32 v[114:115], v[118:119], v[114:115] op_sel_hi:[0,1]
	v_pk_mul_f32 v[118:119], v[122:123], v[178:179] op_sel_hi:[0,1]
	v_pk_mul_f32 v[138:139], v[122:123], v[138:139] op_sel_hi:[0,1]
	v_pk_mul_f32 v[144:145], v[122:123], v[200:201] op_sel_hi:[0,1]
	v_pk_mul_f32 v[140:141], v[122:123], v[140:141] op_sel_hi:[0,1]
	v_pk_mul_f32 v[146:147], v[122:123], v[182:183] op_sel_hi:[0,1]
	v_pk_mul_f32 v[126:127], v[122:123], v[126:127] op_sel_hi:[0,1]
	v_pk_mul_f32 v[148:149], v[122:123], v[170:171] op_sel_hi:[0,1]
	v_pk_mul_f32 v[122:123], v[122:123], v[136:137] op_sel_hi:[0,1]
	v_pk_fma_f32 v[136:137], v[34:35], v[120:121], v[18:19]
	v_pk_fma_f32 v[150:151], v[36:37], v[124:125], v[16:17]
	v_pk_fma_f32 v[152:153], v[50:51], v[110:111], v[2:3]
	v_pk_fma_f32 v[110:111], v[54:55], v[110:111], v[10:11]
	v_pk_fma_f32 v[156:157], v[62:63], v[112:113], v[6:7]
	v_pk_fma_f32 v[158:159], v[64:65], v[116:117], v[4:5]
	v_pk_fma_f32 v[168:169], v[74:75], v[114:115], v[22:23]
	v_pk_fma_f32 v[170:171], v[76:77], v[92:93], v[20:21]
	v_pk_fma_f32 v[114:115], v[78:79], v[114:115], v[30:31]
	v_pk_fma_f32 v[92:93], v[80:81], v[92:93], v[28:29]
	v_pk_fma_f32 v[128:129], v[38:39], v[138:139], v[128:129]
	v_pk_fma_f32 v[118:119], v[40:41], v[118:119], v[160:161]
	v_pk_fma_f32 v[130:131], v[46:47], v[140:141], v[130:131]
	v_pk_fma_f32 v[138:139], v[48:49], v[144:145], v[162:163]
	v_pk_fma_f32 v[126:127], v[58:59], v[126:127], v[132:133]
	v_pk_fma_f32 v[122:123], v[70:71], v[122:123], v[134:135]
	v_pk_fma_f32 v[134:135], v[72:73], v[148:149], v[166:167]
	v_pk_fma_f32 v[120:121], v[42:43], v[120:121], v[26:27]
	v_pk_fma_f32 v[124:125], v[44:45], v[124:125], v[24:25]
	v_pk_fma_f32 v[154:155], v[52:53], v[142:143], v[0:1]
	v_pk_fma_f32 v[142:143], v[56:57], v[142:143], v[8:9]
	v_pk_fma_f32 v[112:113], v[66:67], v[112:113], v[14:15]
	v_pk_fma_f32 v[116:117], v[68:69], v[116:117], v[12:13]
	v_pk_fma_f32 v[132:133], v[60:61], v[146:147], v[164:165]
	v_cvt_pk_bf16_f32 v140, v150, v151
	v_cvt_pk_bf16_f32 v141, v136, v137
	v_cvt_pk_bf16_f32 v137, v110, v111
	v_cvt_pk_bf16_f32 v110, v158, v159
	v_cvt_pk_bf16_f32 v111, v156, v157
	v_cvt_pk_bf16_f32 v92, v92, v93
	v_cvt_pk_bf16_f32 v93, v114, v115
	v_cvt_pk_bf16_f32 v114, v118, v119
	v_cvt_pk_bf16_f32 v115, v128, v129
	v_cvt_pk_bf16_f32 v118, v138, v139
	v_cvt_pk_bf16_f32 v119, v130, v131
	v_cvt_pk_bf16_f32 v129, v126, v127
	v_cvt_pk_bf16_f32 v126, v134, v135
	v_cvt_pk_bf16_f32 v127, v122, v123
	v_cvt_pk_bf16_f32 v124, v124, v125
	v_cvt_pk_bf16_f32 v125, v120, v121
	v_cvt_pk_bf16_f32 v120, v154, v155
	v_cvt_pk_bf16_f32 v121, v152, v153
	v_cvt_pk_bf16_f32 v136, v142, v143
	v_cvt_pk_bf16_f32 v116, v116, v117
	v_cvt_pk_bf16_f32 v117, v112, v113
	v_cvt_pk_bf16_f32 v112, v170, v171
	v_cvt_pk_bf16_f32 v113, v168, v169
	v_cvt_pk_bf16_f32 v128, v132, v133
	global_store_dwordx2 v[98:99], v[140:141], off
	global_store_dwordx2 v[100:101], v[124:125], off
	global_store_dwordx2 v[98:99], v[120:121], off offset:512
	global_store_dwordx2 v[100:101], v[136:137], off offset:512
	global_store_dwordx2 v[98:99], v[110:111], off offset:1024
	global_store_dwordx2 v[100:101], v[116:117], off offset:1024
	global_store_dwordx2 v[98:99], v[112:113], off offset:1536
	global_store_dwordx2 v[100:101], v[92:93], off offset:1536
	global_store_dwordx2 v[102:103], v[114:115], off nt
	global_store_dwordx2 v[102:103], v[118:119], off offset:512 nt
	global_store_dwordx2 v[102:103], v[128:129], off offset:1024 nt
	global_store_dwordx2 v[102:103], v[126:127], off offset:1536 nt
	v_lshlrev_b32_e32 v103, 16, v115
	v_lshlrev_b32_e32 v102, 16, v114
	v_and_b32_e32 v111, 0xffff0000, v115
	v_and_b32_e32 v110, 0xffff0000, v114
	v_and_b32_e32 v115, 0xffff0000, v119
	v_and_b32_e32 v114, 0xffff0000, v118
	v_lshlrev_b32_e32 v92, 16, v128
	v_and_b32_e32 v93, 0xffff0000, v128
	v_lshlrev_b32_e32 v98, 16, v126
	v_lshlrev_b32_e32 v113, 16, v119
	v_lshlrev_b32_e32 v112, 16, v118
	v_lshlrev_b32_e32 v116, 16, v129
	v_pk_mul_f32 v[118:119], v[110:111], v[110:111]
	v_pk_mul_f32 v[120:121], v[114:115], v[114:115]
	v_and_b32_e32 v117, 0xffff0000, v129
	v_mul_f32_e32 v99, v92, v92
	v_mul_f32_e32 v123, v93, v93
	v_mul_f32_e32 v124, v116, v116
	v_mov_b32_e32 v122, v98
	v_mov_b32_e32 v128, v102
	v_mov_b32_e32 v129, v110
	v_mov_b32_e32 v110, v103
	v_mov_b32_e32 v130, v112
	v_mov_b32_e32 v131, v114
	v_mov_b32_e32 v114, v113
	v_pk_fma_f32 v[102:103], v[102:103], v[102:103], v[118:119]
	v_pk_fma_f32 v[112:113], v[112:113], v[112:113], v[120:121]
	v_and_b32_e32 v109, 0xffff0000, v126
	v_lshlrev_b32_e32 v100, 16, v127
	v_and_b32_e32 v101, 0xffff0000, v127
	v_pk_fma_f32 v[118:119], v[116:117], v[116:117], v[124:125] op_sel_hi:[1,1,0]
	v_pk_add_f32 v[120:121], v[98:99], v[122:123]
	v_pk_add_f32 v[102:103], v[102:103], v[102:103] op_sel_hi:[0,1]
	v_pk_add_f32 v[112:113], v[112:113], v[112:113] op_sel_hi:[0,1]
	v_mul_f32_e32 v126, v98, v98
	v_mul_f32_e32 v118, v109, v109
	v_mov_b32_e32 v127, v121
	v_mul_f32_e32 v102, v100, v100
	v_mul_f32_e32 v112, v101, v101
	v_pk_add_f32 v[118:119], v[126:127], v[118:119]
	v_pk_add_f32 v[102:103], v[102:103], v[112:113]
	v_mov_b32_e32 v99, v109
	v_pk_add_f32 v[102:103], v[118:119], v[102:103]
	s_nop 0
	v_add_f32_e32 v102, v102, v103
	s_nop 1
	v_add_f32_dpp v102, v102, v102 row_shr:1 row_mask:0xf bank_mask:0xf
	s_nop 1
	v_add_f32_dpp v102, v102, v102 row_shr:2 row_mask:0xf bank_mask:0xf
	s_nop 1
	v_add_f32_dpp v102, v102, v102 row_shr:4 row_mask:0xf bank_mask:0xf
	s_nop 1
	v_add_f32_dpp v102, v102, v102 row_shr:8 row_mask:0xf bank_mask:0xf
	s_nop 1
	v_add_f32_dpp v102, v102, v102 row_bcast:15 row_mask:0xa bank_mask:0xf
	s_nop 1
	v_add_f32_dpp v102, v102, v102 row_bcast:31 row_mask:0xc bank_mask:0xf
	s_nop 1
	v_readlane_b32 s98, v102, 63
	v_mov_b32_e32 v102, s98
	v_fmamk_f32 v102, v102, 0x3a800000, v90
	v_mul_f32_e32 v103, 0x4b800000, v102
	v_cmp_gt_f32_e32 vcc, s18, v102
	s_nop 1
	v_cndmask_b32_e32 v102, v102, v103, vcc
	v_rsq_f32_e32 v102, v102
	s_nop 0
	v_mul_f32_e32 v103, 0x45800000, v102
	v_cndmask_b32_e32 v102, v102, v103, vcc
	v_pk_mul_f32 v[112:113], v[102:103], v[128:129] op_sel_hi:[0,1]
	v_pk_mul_f32 v[110:111], v[102:103], v[110:111] op_sel_hi:[0,1]
	v_pk_mul_f32 v[118:119], v[102:103], v[130:131] op_sel_hi:[0,1]
	v_pk_mul_f32 v[114:115], v[102:103], v[114:115] op_sel_hi:[0,1]
	v_pk_mul_f32 v[92:93], v[102:103], v[92:93] op_sel_hi:[0,1]
	v_pk_mul_f32 v[116:117], v[102:103], v[116:117] op_sel_hi:[0,1]
	v_pk_mul_f32 v[98:99], v[102:103], v[98:99] op_sel_hi:[0,1]
	v_pk_mul_f32 v[100:101], v[102:103], v[100:101] op_sel_hi:[0,1]
	v_pk_fma_f32 v[102:103], v[34:35], v[110:111], v[18:19]
	v_pk_fma_f32 v[120:121], v[36:37], v[112:113], v[16:17]
	v_pk_fma_f32 v[110:111], v[42:43], v[110:111], v[26:27]
	v_pk_fma_f32 v[112:113], v[44:45], v[112:113], v[24:25]
	v_pk_fma_f32 v[122:123], v[50:51], v[114:115], v[2:3]
	v_pk_fma_f32 v[124:125], v[52:53], v[118:119], v[0:1]
	v_pk_fma_f32 v[114:115], v[54:55], v[114:115], v[10:11]
	v_pk_fma_f32 v[118:119], v[56:57], v[118:119], v[8:9]
	v_pk_fma_f32 v[126:127], v[62:63], v[116:117], v[6:7]
	v_pk_fma_f32 v[128:129], v[64:65], v[92:93], v[4:5]
	v_pk_fma_f32 v[116:117], v[66:67], v[116:117], v[14:15]
	v_pk_fma_f32 v[92:93], v[68:69], v[92:93], v[12:13]
	v_pk_fma_f32 v[130:131], v[74:75], v[100:101], v[22:23]
	v_pk_fma_f32 v[132:133], v[76:77], v[98:99], v[20:21]
	v_pk_fma_f32 v[100:101], v[78:79], v[100:101], v[30:31]
	v_pk_fma_f32 v[98:99], v[80:81], v[98:99], v[28:29]
	v_cvt_pk_bf16_f32 v120, v120, v121
	v_cvt_pk_bf16_f32 v121, v102, v103
	v_cvt_pk_bf16_f32 v102, v112, v113
	v_cvt_pk_bf16_f32 v103, v110, v111
	v_cvt_pk_bf16_f32 v110, v124, v125
	v_cvt_pk_bf16_f32 v111, v122, v123
	v_cvt_pk_bf16_f32 v112, v118, v119
	v_cvt_pk_bf16_f32 v113, v114, v115
	v_cvt_pk_bf16_f32 v114, v128, v129
	v_cvt_pk_bf16_f32 v115, v126, v127
	v_cvt_pk_bf16_f32 v92, v92, v93
	v_cvt_pk_bf16_f32 v93, v116, v117
	v_cvt_pk_bf16_f32 v116, v132, v133
	v_cvt_pk_bf16_f32 v117, v130, v131
	v_cvt_pk_bf16_f32 v98, v98, v99
	v_cvt_pk_bf16_f32 v99, v100, v101
	global_store_dwordx2 v[94:95], v[120:121], off
	global_store_dwordx2 v[96:97], v[102:103], off
	global_store_dwordx2 v[94:95], v[110:111], off offset:512
	global_store_dwordx2 v[96:97], v[112:113], off offset:512
	global_store_dwordx2 v[94:95], v[114:115], off offset:1024
	global_store_dwordx2 v[96:97], v[92:93], off offset:1024
	global_store_dwordx2 v[94:95], v[116:117], off offset:1536
	global_store_dwordx2 v[96:97], v[98:99], off offset:1536
	s_cbranch_scc1 .LBB0_980

.LBB0_1498:
	v_lshl_add_u64 v[60:61], s[6:7], 0, v[16:17]
	v_add_co_u32_e64 v80, s[0:1], s17, v60
	v_lshl_add_u64 v[62:63], s[8:9], 0, v[16:17]
	s_nop 0
	v_addc_co_u32_e64 v81, s[0:1], 0, v61, s[0:1]
	s_add_i32 s12, s15, s14
	v_add_co_u32_e32 v64, vcc, 0x4000000, v60
	global_load_dwordx2 v[72:73], v[62:63], off nt
	global_load_dwordx2 v[74:75], v[62:63], off offset:512 nt
	global_load_dwordx2 v[76:77], v[62:63], off offset:1024 nt
	global_load_dwordx2 v[78:79], v[62:63], off offset:1536 nt
	v_add_co_u32_e64 v62, s[0:1], s18, v60
	s_ashr_i32 s13, s12, 31
	s_nop 0
	v_addc_co_u32_e64 v63, s[0:1], 0, v61, s[0:1]
	v_addc_co_u32_e32 v65, vcc, 0, v61, vcc
	s_lshl_b64 s[0:1], s[12:13], 11
	global_load_dwordx2 v[82:83], v[64:65], off offset:1536 nt
	global_load_dwordx2 v[84:85], v[64:65], off nt
	global_load_dwordx2 v[86:87], v[64:65], off offset:512 nt
	global_load_dwordx2 v[88:89], v[64:65], off offset:1024 nt
	v_lshl_add_u64 v[90:91], v[18:19], 0, s[0:1]
	v_lshl_add_u64 v[92:93], v[20:21], 0, s[0:1]
	global_load_dwordx2 v[94:95], v[90:91], off nt
	global_load_dwordx2 v[96:97], v[90:91], off offset:512 nt
	global_load_dwordx2 v[98:99], v[90:91], off offset:1024 nt
	global_load_dwordx2 v[100:101], v[90:91], off offset:1536 nt
	global_load_dwordx2 v[102:103], v[92:93], off offset:1536 nt
	global_load_dwordx2 v[104:105], v[92:93], off nt
	global_load_dwordx2 v[106:107], v[92:93], off offset:512 nt
	global_load_dwordx2 v[108:109], v[92:93], off offset:1024 nt
	v_lshl_add_u64 v[64:65], v[54:55], 0, s[0:1]
	v_lshl_add_u64 v[60:61], v[56:57], 0, s[0:1]
	s_add_i32 s14, s14, 2
	s_add_u32 s6, s6, 0x1000
	s_addc_u32 s7, s7, 0
	s_add_u32 s8, s8, 0x1000
	s_addc_u32 s9, s9, 0
	s_cmp_lt_i32 s14, s11
	s_waitcnt vmcnt(15)
	v_lshlrev_b32_e32 v90, 16, v72
	v_and_b32_e32 v91, 0xffff0000, v72
	v_lshlrev_b32_e32 v72, 16, v73
	v_and_b32_e32 v73, 0xffff0000, v73
	s_waitcnt vmcnt(14)
	v_lshlrev_b32_e32 v92, 16, v74
	v_and_b32_e32 v93, 0xffff0000, v74
	v_lshlrev_b32_e32 v74, 16, v75
	v_and_b32_e32 v75, 0xffff0000, v75
	s_waitcnt vmcnt(13)
	v_lshlrev_b32_e32 v110, 16, v76
	s_waitcnt vmcnt(11)
	v_lshlrev_b32_e32 v115, 16, v82
	s_waitcnt vmcnt(10)
	v_lshlrev_b32_e32 v118, 16, v84
	v_and_b32_e32 v119, 0xffff0000, v84
	v_lshlrev_b32_e32 v84, 16, v85
	v_and_b32_e32 v85, 0xffff0000, v85
	s_waitcnt vmcnt(9)
	v_lshlrev_b32_e32 v121, 16, v87
	v_lshlrev_b32_e32 v120, 16, v86
	v_and_b32_e32 v87, 0xffff0000, v87
	v_and_b32_e32 v86, 0xffff0000, v86
	s_waitcnt vmcnt(8)
	v_lshlrev_b32_e32 v122, 16, v88
	v_and_b32_e32 v123, 0xffff0000, v88
	v_lshlrev_b32_e32 v88, 16, v89
	v_and_b32_e32 v89, 0xffff0000, v89
	s_waitcnt vmcnt(3)
	v_lshlrev_b32_e32 v133, 16, v102
	v_mul_f32_e32 v114, v85, v85
	v_pk_mul_f32 v[136:137], v[86:87], v[86:87]
	v_mul_f32_e32 v132, v119, v119
	v_mov_b32_e32 v139, v115
	v_mul_f32_e32 v138, v89, v89
	v_mov_b32_e32 v140, v120
	v_mov_b32_e32 v141, v86
	v_mov_b32_e32 v86, v121
	s_waitcnt vmcnt(2)
	v_lshlrev_b32_e32 v142, 16, v104
	v_and_b32_e32 v143, 0xffff0000, v104
	v_lshlrev_b32_e32 v104, 16, v105
	v_and_b32_e32 v105, 0xffff0000, v105
	s_waitcnt vmcnt(1)
	v_lshlrev_b32_e32 v145, 16, v107
	v_lshlrev_b32_e32 v144, 16, v106
	v_and_b32_e32 v107, 0xffff0000, v107
	v_and_b32_e32 v106, 0xffff0000, v106
	v_pk_fma_f32 v[148:149], v[84:85], v[84:85], v[114:115] op_sel_hi:[1,1,0]
	v_pk_fma_f32 v[120:121], v[120:121], v[120:121], v[136:137]
	v_pk_fma_f32 v[136:137], v[118:119], v[118:119], v[132:133] op_sel_hi:[1,1,0]
	v_and_b32_e32 v117, 0xffff0000, v82
	v_lshlrev_b32_e32 v82, 16, v83
	v_and_b32_e32 v83, 0xffff0000, v83
	v_and_b32_e32 v135, 0xffff0000, v102
	v_mul_f32_e32 v134, v123, v123
	v_pk_fma_f32 v[152:153], v[88:89], v[88:89], v[138:139] op_sel_hi:[1,1,0]
	v_mul_f32_e32 v132, v105, v105
	v_pk_mul_f32 v[154:155], v[106:107], v[106:107]
	v_mul_f32_e32 v156, v143, v143
	v_mov_b32_e32 v157, v133
	v_mov_b32_e32 v114, v136
	v_mov_b32_e32 v138, v148
	v_mul_f32_e32 v71, v117, v117
	v_mul_f32_e32 v159, v82, v82
	v_mul_f32_e32 v161, v83, v83
	v_mov_b32_e32 v116, v115
	s_waitcnt vmcnt(0)
	v_lshlrev_b32_e32 v146, 16, v108
	v_and_b32_e32 v147, 0xffff0000, v108
	v_lshlrev_b32_e32 v108, 16, v109
	v_and_b32_e32 v109, 0xffff0000, v109
	v_pk_fma_f32 v[150:151], v[122:123], v[122:123], v[134:135] op_sel_hi:[1,1,0]
	v_mov_b32_e32 v162, v144
	v_mov_b32_e32 v163, v106
	v_mov_b32_e32 v106, v145
	v_pk_add_f32 v[136:137], v[136:137], v[148:149]
	v_pk_add_f32 v[120:121], v[120:121], v[120:121] op_sel:[0,1] op_sel_hi:[1,0]
	v_pk_fma_f32 v[148:149], v[104:105], v[104:105], v[132:133] op_sel_hi:[1,1,0]
	v_pk_fma_f32 v[144:145], v[144:145], v[144:145], v[154:155]
	v_pk_fma_f32 v[154:155], v[142:143], v[142:143], v[156:157] op_sel_hi:[1,1,0]
	v_pk_mul_f32 v[114:115], v[114:115], v[138:139]
	v_lshlrev_b32_e32 v102, 16, v103
	v_and_b32_e32 v103, 0xffff0000, v103
	v_mul_f32_e32 v158, v147, v147
	v_mul_f32_e32 v160, v109, v109
	v_mov_b32_e32 v151, v159
	v_mov_b32_e32 v153, v161
	v_mov_b32_e32 v121, v71
	v_mov_b32_e32 v132, v154
	v_mov_b32_e32 v156, v148
	v_mov_b32_e32 v137, v115
	v_mul_f32_e32 v164, v135, v135
	v_mul_f32_e32 v165, v102, v102
	v_mul_f32_e32 v166, v103, v103
	v_pk_fma_f32 v[158:159], v[146:147], v[146:147], v[158:159] op_sel_hi:[1,1,0]
	v_pk_fma_f32 v[160:161], v[108:109], v[108:109], v[160:161] op_sel_hi:[1,1,0]
	v_pk_add_f32 v[138:139], v[150:151], v[152:153]
	v_pk_add_f32 v[148:149], v[154:155], v[148:149]
	v_pk_add_f32 v[144:145], v[144:145], v[144:145] op_sel:[0,1] op_sel_hi:[1,0]
	v_pk_mul_f32 v[114:115], v[132:133], v[156:157]
	v_pk_add_f32 v[120:121], v[136:137], v[120:121]
	v_mov_b32_e32 v159, v165
	v_mov_b32_e32 v161, v166
	v_mov_b32_e32 v145, v164
	v_mov_b32_e32 v149, v115
	v_pk_add_f32 v[114:115], v[120:121], v[138:139]
	v_mov_b32_e32 v134, v133
	v_pk_add_f32 v[132:133], v[158:159], v[160:161]
	v_pk_add_f32 v[120:121], v[148:149], v[144:145]
	v_add_f32_e32 v71, v114, v115
	v_pk_add_f32 v[114:115], v[120:121], v[132:133]
	v_mov_b32_e32 v120, v114
	v_and_b32_e32 v111, 0xffff0000, v76
	v_lshlrev_b32_e32 v76, 16, v77
	v_and_b32_e32 v77, 0xffff0000, v77
	v_lshlrev_b32_e32 v112, 16, v78
	v_and_b32_e32 v113, 0xffff0000, v78
	v_lshlrev_b32_e32 v78, 16, v79
	v_and_b32_e32 v79, 0xffff0000, v79
	v_lshlrev_b32_e32 v124, 16, v94
	v_and_b32_e32 v125, 0xffff0000, v94
	v_lshlrev_b32_e32 v94, 16, v95
	v_and_b32_e32 v95, 0xffff0000, v95
	v_lshlrev_b32_e32 v126, 16, v96
	v_and_b32_e32 v127, 0xffff0000, v96
	v_lshlrev_b32_e32 v96, 16, v97
	v_and_b32_e32 v97, 0xffff0000, v97
	v_lshlrev_b32_e32 v128, 16, v98
	v_and_b32_e32 v129, 0xffff0000, v98
	v_lshlrev_b32_e32 v98, 16, v99
	v_and_b32_e32 v99, 0xffff0000, v99
	v_lshlrev_b32_e32 v130, 16, v100
	v_and_b32_e32 v131, 0xffff0000, v100
	v_lshlrev_b32_e32 v100, 16, v101
	v_and_b32_e32 v101, 0xffff0000, v101
	s_nop 1
	v_add_f32_dpp v71, v71, v71 row_shr:1 row_mask:0xf bank_mask:0xf
	s_nop 1
	v_add_f32_dpp v71, v71, v71 row_shr:2 row_mask:0xf bank_mask:0xf
	s_nop 1
	v_add_f32_dpp v71, v71, v71 row_shr:4 row_mask:0xf bank_mask:0xf
	s_nop 1
	v_add_f32_dpp v71, v71, v71 row_shr:8 row_mask:0xf bank_mask:0xf
	s_nop 1
	v_add_f32_dpp v71, v71, v71 row_bcast:15 row_mask:0xa bank_mask:0xf
	s_nop 1
	v_add_f32_dpp v71, v71, v71 row_bcast:31 row_mask:0xc bank_mask:0xf
	s_nop 1
	v_readlane_b32 s98, v71, 63
	v_mov_b32_e32 v71, s98
	v_fmamk_f32 v71, v71, 0x3a800000, v58
	v_mul_f32_e32 v114, 0x4b800000, v71
	v_cmp_gt_f32_e32 vcc, s16, v71
	s_nop 1
	v_cndmask_b32_e32 v71, v71, v114, vcc
	v_rsq_f32_e32 v71, v71
	s_nop 0
	v_mul_f32_e32 v114, 0x45800000, v71
	v_cndmask_b32_e32 v114, v71, v114, vcc
	v_pk_mul_f32 v[118:119], v[114:115], v[118:119] op_sel_hi:[0,1]
	v_pk_mul_f32 v[84:85], v[114:115], v[84:85] op_sel_hi:[0,1]
	v_pk_mul_f32 v[132:133], v[114:115], v[140:141] op_sel_hi:[0,1]
	v_pk_mul_f32 v[86:87], v[114:115], v[86:87] op_sel_hi:[0,1]
	v_pk_mul_f32 v[88:89], v[114:115], v[88:89] op_sel_hi:[0,1]
	v_pk_mul_f32 v[116:117], v[114:115], v[116:117] op_sel_hi:[0,1]
	v_pk_mul_f32 v[82:83], v[114:115], v[82:83] op_sel_hi:[0,1]
	v_pk_mul_f32 v[122:123], v[114:115], v[122:123] op_sel_hi:[0,1]
	v_pk_fma_f32 v[72:73], v[22:23], v[84:85], v[72:73]
	v_pk_fma_f32 v[84:85], v[24:25], v[118:119], v[90:91]
	v_pk_fma_f32 v[74:75], v[26:27], v[86:87], v[74:75]
	v_pk_fma_f32 v[86:87], v[28:29], v[132:133], v[92:93]
	v_pk_fma_f32 v[76:77], v[30:31], v[88:89], v[76:77]
	v_pk_fma_f32 v[78:79], v[34:35], v[82:83], v[78:79]
	v_pk_fma_f32 v[82:83], v[36:37], v[116:117], v[112:113]
	v_pk_fma_f32 v[88:89], v[32:33], v[122:123], v[110:111]
	v_cvt_pk_bf16_f32 v84, v84, v85
	v_cvt_pk_bf16_f32 v85, v72, v73
	v_cvt_pk_bf16_f32 v72, v86, v87
	v_cvt_pk_bf16_f32 v73, v74, v75
	v_cvt_pk_bf16_f32 v75, v76, v77
	v_cvt_pk_bf16_f32 v76, v82, v83
	v_cvt_pk_bf16_f32 v77, v78, v79
	v_cvt_pk_bf16_f32 v74, v88, v89
	global_store_dwordx2 v[80:81], v[84:85], off nt
	global_store_dwordx2 v[80:81], v[72:73], off offset:512 nt
	global_store_dwordx2 v[80:81], v[74:75], off offset:1024 nt
	global_store_dwordx2 v[80:81], v[76:77], off offset:1536 nt
	v_lshlrev_b32_e32 v81, 16, v85
	v_lshlrev_b32_e32 v80, 16, v84
	v_and_b32_e32 v83, 0xffff0000, v85
	v_and_b32_e32 v82, 0xffff0000, v84
	v_lshlrev_b32_e32 v85, 16, v73
	v_lshlrev_b32_e32 v84, 16, v72
	v_and_b32_e32 v73, 0xffff0000, v73
	v_and_b32_e32 v72, 0xffff0000, v72
	v_lshlrev_b32_e32 v78, 16, v74
	v_and_b32_e32 v79, 0xffff0000, v74
	v_lshlrev_b32_e32 v74, 16, v76
	v_lshlrev_b32_e32 v86, 16, v75
	v_pk_mul_f32 v[88:89], v[82:83], v[82:83]
	v_pk_mul_f32 v[90:91], v[72:73], v[72:73]
	v_and_b32_e32 v87, 0xffff0000, v75
	v_mul_f32_e32 v75, v78, v78
	v_mul_f32_e32 v93, v79, v79
	v_mul_f32_e32 v110, v86, v86
	v_mov_b32_e32 v92, v74
	v_mov_b32_e32 v116, v80
	v_mov_b32_e32 v117, v82
	v_mov_b32_e32 v82, v81
	v_mov_b32_e32 v118, v84
	v_mov_b32_e32 v119, v72
	v_mov_b32_e32 v72, v85
	v_pk_fma_f32 v[80:81], v[80:81], v[80:81], v[88:89]
	v_pk_fma_f32 v[84:85], v[84:85], v[84:85], v[90:91]
	v_and_b32_e32 v71, 0xffff0000, v76
	v_lshlrev_b32_e32 v76, 16, v77
	v_and_b32_e32 v77, 0xffff0000, v77
	v_pk_fma_f32 v[88:89], v[86:87], v[86:87], v[110:111] op_sel_hi:[1,1,0]
	v_pk_add_f32 v[90:91], v[74:75], v[92:93]
	v_pk_add_f32 v[80:81], v[80:81], v[80:81] op_sel_hi:[0,1]
	v_pk_add_f32 v[84:85], v[84:85], v[84:85] op_sel_hi:[0,1]
	v_mul_f32_e32 v112, v74, v74
	v_mul_f32_e32 v88, v71, v71
	v_mov_b32_e32 v113, v91
	v_mul_f32_e32 v80, v76, v76
	v_mul_f32_e32 v84, v77, v77
	v_pk_add_f32 v[88:89], v[112:113], v[88:89]
	v_pk_add_f32 v[80:81], v[80:81], v[84:85]
	v_mov_b32_e32 v75, v71
	v_pk_add_f32 v[80:81], v[88:89], v[80:81]
	s_nop 0
	v_mov_b32_e32 v121, v80
	v_mov_b32_e32 v80, v115
	v_pk_add_f32 v[80:81], v[120:121], v[80:81]
	s_nop 1
	v_add_f32_dpp v80, v80, v80 row_shr:1 row_mask:0xf bank_mask:0xf
	v_add_f32_dpp v81, v81, v81 row_shr:1 row_mask:0xf bank_mask:0xf
	s_nop 0
	v_add_f32_dpp v80, v80, v80 row_shr:2 row_mask:0xf bank_mask:0xf
	v_add_f32_dpp v81, v81, v81 row_shr:2 row_mask:0xf bank_mask:0xf
	s_nop 0
	v_add_f32_dpp v80, v80, v80 row_shr:4 row_mask:0xf bank_mask:0xf
	v_add_f32_dpp v81, v81, v81 row_shr:4 row_mask:0xf bank_mask:0xf
	s_nop 0
	v_add_f32_dpp v80, v80, v80 row_shr:8 row_mask:0xf bank_mask:0xf
	v_add_f32_dpp v81, v81, v81 row_shr:8 row_mask:0xf bank_mask:0xf
	s_nop 0
	v_add_f32_dpp v80, v80, v80 row_bcast:15 row_mask:0xa bank_mask:0xf
	v_add_f32_dpp v81, v81, v81 row_bcast:15 row_mask:0xa bank_mask:0xf
	s_nop 0
	v_add_f32_dpp v80, v80, v80 row_bcast:31 row_mask:0xc bank_mask:0xf
	v_add_f32_dpp v81, v81, v81 row_bcast:31 row_mask:0xc bank_mask:0xf
	s_nop 0
	s_nop 0
	v_readlane_b32 s98, v80, 63
	v_readlane_b32 s99, v81, 63
	v_mov_b32_e32 v80, s98
	v_mov_b32_e32 v81, s99
	s_nop 0
	v_pk_fma_f32 v[80:81], v[80:81], s[10:11], v[58:59] op_sel_hi:[1,0,0]
	s_nop 0
	v_mul_f32_e32 v71, 0x4b800000, v81
	v_mul_f32_e32 v84, 0x4b800000, v80
	v_cmp_gt_f32_e32 vcc, s16, v80
	v_cmp_gt_f32_e64 s[0:1], s16, v81
	s_nop 0
	v_cndmask_b32_e32 v80, v80, v84, vcc
	v_cndmask_b32_e64 v71, v81, v71, s[0:1]
	v_rsq_f32_e32 v71, v71
	v_rsq_f32_e32 v81, v80
	v_mul_f32_e32 v80, 0x45800000, v71
	v_mul_f32_e32 v84, 0x45800000, v81
	v_cndmask_b32_e64 v80, v71, v80, s[0:1]
	v_cndmask_b32_e32 v84, v81, v84, vcc
	v_pk_mul_f32 v[88:89], v[80:81], v[116:117] op_sel_hi:[0,1]
	v_pk_mul_f32 v[82:83], v[80:81], v[82:83] op_sel_hi:[0,1]
	v_pk_mul_f32 v[90:91], v[80:81], v[118:119] op_sel_hi:[0,1]
	v_pk_mul_f32 v[72:73], v[80:81], v[72:73] op_sel_hi:[0,1]
	v_pk_mul_f32 v[78:79], v[80:81], v[78:79] op_sel_hi:[0,1]
	v_pk_mul_f32 v[86:87], v[80:81], v[86:87] op_sel_hi:[0,1]
	v_pk_mul_f32 v[74:75], v[80:81], v[74:75] op_sel_hi:[0,1]
	v_pk_mul_f32 v[76:77], v[80:81], v[76:77] op_sel_hi:[0,1]
	v_pk_mul_f32 v[80:81], v[84:85], v[142:143] op_sel_hi:[0,1]
	v_pk_mul_f32 v[92:93], v[84:85], v[104:105] op_sel_hi:[0,1]
	v_pk_mul_f32 v[104:105], v[84:85], v[162:163] op_sel_hi:[0,1]
	v_pk_mul_f32 v[106:107], v[84:85], v[106:107] op_sel_hi:[0,1]
	v_pk_mul_f32 v[110:111], v[84:85], v[146:147] op_sel_hi:[0,1]
	v_pk_mul_f32 v[108:109], v[84:85], v[108:109] op_sel_hi:[0,1]
	v_pk_mul_f32 v[112:113], v[84:85], v[134:135] op_sel_hi:[0,1]
	v_pk_mul_f32 v[84:85], v[84:85], v[102:103] op_sel_hi:[0,1]
	v_pk_fma_f32 v[82:83], v[38:39], v[82:83], v[2:3]
	v_pk_fma_f32 v[88:89], v[40:41], v[88:89], v[0:1]
	v_pk_fma_f32 v[72:73], v[42:43], v[72:73], v[6:7]
	v_pk_fma_f32 v[90:91], v[44:45], v[90:91], v[4:5]
	v_pk_fma_f32 v[78:79], v[48:49], v[78:79], v[8:9]
	v_pk_fma_f32 v[76:77], v[50:51], v[76:77], v[14:15]
	v_pk_fma_f32 v[74:75], v[52:53], v[74:75], v[12:13]
	v_pk_fma_f32 v[92:93], v[22:23], v[92:93], v[94:95]
	v_pk_fma_f32 v[80:81], v[24:25], v[80:81], v[124:125]
	v_pk_fma_f32 v[94:95], v[26:27], v[106:107], v[96:97]
	v_pk_fma_f32 v[96:97], v[28:29], v[104:105], v[126:127]
	v_pk_fma_f32 v[86:87], v[46:47], v[86:87], v[10:11]
	v_pk_fma_f32 v[98:99], v[30:31], v[108:109], v[98:99]
	v_pk_fma_f32 v[102:103], v[32:33], v[110:111], v[128:129]
	v_pk_fma_f32 v[84:85], v[34:35], v[84:85], v[100:101]
	v_pk_fma_f32 v[100:101], v[36:37], v[112:113], v[130:131]
	v_cvt_pk_bf16_f32 v88, v88, v89
	v_cvt_pk_bf16_f32 v89, v82, v83
	v_cvt_pk_bf16_f32 v82, v90, v91
	v_cvt_pk_bf16_f32 v83, v72, v73
	v_cvt_pk_bf16_f32 v72, v78, v79
	v_cvt_pk_bf16_f32 v74, v74, v75
	v_cvt_pk_bf16_f32 v75, v76, v77
	v_cvt_pk_bf16_f32 v76, v80, v81
	v_cvt_pk_bf16_f32 v77, v92, v93
	v_cvt_pk_bf16_f32 v78, v96, v97
	v_cvt_pk_bf16_f32 v79, v94, v95
	v_cvt_pk_bf16_f32 v73, v86, v87
	v_cvt_pk_bf16_f32 v80, v102, v103
	v_cvt_pk_bf16_f32 v81, v98, v99
	v_cvt_pk_bf16_f32 v86, v100, v101
	v_cvt_pk_bf16_f32 v87, v84, v85
	global_store_dwordx2 v[62:63], v[88:89], off
	global_store_dwordx2 v[62:63], v[82:83], off offset:512
	global_store_dwordx2 v[62:63], v[72:73], off offset:1024
	global_store_dwordx2 v[62:63], v[74:75], off offset:1536
	global_store_dwordx2 v[64:65], v[76:77], off nt
	global_store_dwordx2 v[64:65], v[78:79], off offset:512 nt
	global_store_dwordx2 v[64:65], v[80:81], off offset:1024 nt
	v_lshlrev_b32_e32 v75, 16, v77
	v_lshlrev_b32_e32 v74, 16, v76
	v_and_b32_e32 v77, 0xffff0000, v77
	v_and_b32_e32 v76, 0xffff0000, v76
	v_lshlrev_b32_e32 v83, 16, v79
	v_lshlrev_b32_e32 v82, 16, v78
	v_and_b32_e32 v79, 0xffff0000, v79
	v_and_b32_e32 v78, 0xffff0000, v78
	v_lshlrev_b32_e32 v62, 16, v80
	v_and_b32_e32 v63, 0xffff0000, v80
	global_store_dwordx2 v[64:65], v[86:87], off offset:1536 nt
	v_lshlrev_b32_e32 v64, 16, v86
	v_and_b32_e32 v71, 0xffff0000, v86
	v_lshlrev_b32_e32 v72, 16, v87
	v_and_b32_e32 v73, 0xffff0000, v87
	v_lshlrev_b32_e32 v80, 16, v81
	v_pk_mul_f32 v[84:85], v[76:77], v[76:77]
	v_pk_mul_f32 v[86:87], v[78:79], v[78:79]
	v_and_b32_e32 v81, 0xffff0000, v81
	v_mul_f32_e32 v65, v62, v62
	v_mul_f32_e32 v89, v63, v63
	v_mul_f32_e32 v90, v80, v80
	v_mov_b32_e32 v88, v64
	v_mov_b32_e32 v94, v74
	v_mov_b32_e32 v95, v76
	v_mov_b32_e32 v76, v75
	v_mov_b32_e32 v96, v82
	v_mov_b32_e32 v97, v78
	v_mov_b32_e32 v78, v83
	v_pk_fma_f32 v[74:75], v[74:75], v[74:75], v[84:85]
	v_pk_fma_f32 v[82:83], v[82:83], v[82:83], v[86:87]
	v_pk_fma_f32 v[84:85], v[80:81], v[80:81], v[90:91] op_sel_hi:[1,1,0]
	v_pk_add_f32 v[86:87], v[64:65], v[88:89]
	v_pk_add_f32 v[74:75], v[74:75], v[74:75] op_sel_hi:[0,1]
	v_pk_add_f32 v[82:83], v[82:83], v[82:83] op_sel_hi:[0,1]
	v_mul_f32_e32 v92, v64, v64
	v_mul_f32_e32 v84, v71, v71
	v_mov_b32_e32 v93, v87
	v_mul_f32_e32 v74, v72, v72
	v_mul_f32_e32 v82, v73, v73
	v_pk_add_f32 v[84:85], v[92:93], v[84:85]
	v_pk_add_f32 v[74:75], v[74:75], v[82:83]
	v_mov_b32_e32 v65, v71
	v_pk_add_f32 v[74:75], v[84:85], v[74:75]
	s_nop 0
	v_add_f32_e32 v71, v74, v75
	s_nop 1
	v_add_f32_dpp v71, v71, v71 row_shr:1 row_mask:0xf bank_mask:0xf
	s_nop 1
	v_add_f32_dpp v71, v71, v71 row_shr:2 row_mask:0xf bank_mask:0xf
	s_nop 1
	v_add_f32_dpp v71, v71, v71 row_shr:4 row_mask:0xf bank_mask:0xf
	s_nop 1
	v_add_f32_dpp v71, v71, v71 row_shr:8 row_mask:0xf bank_mask:0xf
	s_nop 1
	v_add_f32_dpp v71, v71, v71 row_bcast:15 row_mask:0xa bank_mask:0xf
	s_nop 1
	v_add_f32_dpp v71, v71, v71 row_bcast:31 row_mask:0xc bank_mask:0xf
	s_nop 1
	v_readlane_b32 s98, v71, 63
	v_mov_b32_e32 v71, s98
	v_fmamk_f32 v71, v71, 0x3a800000, v58
	v_mul_f32_e32 v74, 0x4b800000, v71
	v_cmp_gt_f32_e32 vcc, s16, v71
	s_nop 1
	v_cndmask_b32_e32 v71, v71, v74, vcc
	v_rsq_f32_e32 v71, v71
	s_nop 0
	v_mul_f32_e32 v74, 0x45800000, v71
	v_cndmask_b32_e32 v74, v71, v74, vcc
	v_pk_mul_f32 v[82:83], v[74:75], v[94:95] op_sel_hi:[0,1]
	v_pk_mul_f32 v[76:77], v[74:75], v[76:77] op_sel_hi:[0,1]
	v_pk_mul_f32 v[84:85], v[74:75], v[96:97] op_sel_hi:[0,1]
	v_pk_mul_f32 v[78:79], v[74:75], v[78:79] op_sel_hi:[0,1]
	v_pk_mul_f32 v[62:63], v[74:75], v[62:63] op_sel_hi:[0,1]
	v_pk_mul_f32 v[80:81], v[74:75], v[80:81] op_sel_hi:[0,1]
	v_pk_mul_f32 v[64:65], v[74:75], v[64:65] op_sel_hi:[0,1]
	v_pk_mul_f32 v[72:73], v[74:75], v[72:73] op_sel_hi:[0,1]
	v_pk_fma_f32 v[74:75], v[38:39], v[76:77], v[2:3]
	v_pk_fma_f32 v[76:77], v[40:41], v[82:83], v[0:1]
	v_pk_fma_f32 v[78:79], v[42:43], v[78:79], v[6:7]
	v_pk_fma_f32 v[82:83], v[44:45], v[84:85], v[4:5]
	v_pk_fma_f32 v[80:81], v[46:47], v[80:81], v[10:11]
	v_pk_fma_f32 v[62:63], v[48:49], v[62:63], v[8:9]
	v_pk_fma_f32 v[72:73], v[50:51], v[72:73], v[14:15]
	v_pk_fma_f32 v[64:65], v[52:53], v[64:65], v[12:13]
	v_cvt_pk_bf16_f32 v76, v76, v77
	v_cvt_pk_bf16_f32 v77, v74, v75
	v_cvt_pk_bf16_f32 v74, v82, v83
	v_cvt_pk_bf16_f32 v75, v78, v79
	v_cvt_pk_bf16_f32 v62, v62, v63
	v_cvt_pk_bf16_f32 v63, v80, v81
	v_cvt_pk_bf16_f32 v64, v64, v65
	v_cvt_pk_bf16_f32 v65, v72, v73
	global_store_dwordx2 v[60:61], v[76:77], off
	global_store_dwordx2 v[60:61], v[74:75], off offset:512
	global_store_dwordx2 v[60:61], v[62:63], off offset:1024
	global_store_dwordx2 v[60:61], v[64:65], off offset:1536
	s_cbranch_scc1 .LBB0_1498

.LBB0_1714:
	v_add_co_u32_e32 v36, vcc, 0xf8000000, v6
	s_add_i32 s0, s9, s8
	s_nop 0
	v_addc_co_u32_e32 v37, vcc, -1, v7, vcc
	v_add_co_u32_e32 v44, vcc, 0xf8001000, v6
	global_load_dwordx2 v[28:29], v[6:7], off nt
	global_load_dwordx2 v[30:31], v[6:7], off offset:512 nt
	global_load_dwordx2 v[32:33], v[6:7], off offset:1024 nt
	global_load_dwordx2 v[34:35], v[6:7], off offset:1536 nt
	s_ashr_i32 s1, s0, 31
	global_load_dwordx2 v[36:37], v[36:37], off nt
	v_addc_co_u32_e32 v45, vcc, -1, v7, vcc
	s_lshl_b64 s[12:13], s[0:1], 11
	global_load_dwordx2 v[46:47], v[44:45], off offset:-2560 nt
	global_load_dwordx2 v[48:49], v[44:45], off offset:-3584 nt
	global_load_dwordx2 v[50:51], v[44:45], off offset:-3072 nt
	v_lshl_add_u64 v[44:45], v[0:1], 0, s[12:13]
	v_lshl_add_u64 v[52:53], v[2:3], 0, s[12:13]
	global_load_dwordx2 v[54:55], v[44:45], off nt
	global_load_dwordx2 v[56:57], v[44:45], off offset:512 nt
	global_load_dwordx2 v[58:59], v[44:45], off offset:1024 nt
	global_load_dwordx2 v[60:61], v[44:45], off offset:1536 nt
	global_load_dwordx2 v[62:63], v[52:53], off offset:1536 nt
	global_load_dwordx2 v[64:65], v[52:53], off nt
	global_load_dwordx2 v[66:67], v[52:53], off offset:512 nt
	global_load_dwordx2 v[70:71], v[52:53], off offset:1024 nt
	s_lshl_b64 s[0:1], s[0:1], 12
	v_lshl_add_u64 v[68:69], v[4:5], 0, s[0:1]
	s_add_i32 s8, s8, 2
	v_lshl_add_u64 v[6:7], v[6:7], 0, s[4:5]
	s_cmp_lt_i32 s8, s3
	s_waitcnt vmcnt(14)
	v_lshlrev_b32_e32 v72, 16, v31
	v_and_b32_e32 v73, 0xffff0000, v31
	s_waitcnt vmcnt(13)
	v_lshlrev_b32_e32 v76, 16, v33
	v_and_b32_e32 v77, 0xffff0000, v33
	s_waitcnt vmcnt(11)
	v_and_b32_e32 v31, 0xffff0000, v36
	v_and_b32_e32 v33, 0xffff0000, v37
	v_lshlrev_b32_e32 v52, 16, v30
	v_and_b32_e32 v53, 0xffff0000, v30
	v_lshlrev_b32_e32 v74, 16, v32
	v_and_b32_e32 v75, 0xffff0000, v32
	v_lshlrev_b32_e32 v78, 16, v34
	v_and_b32_e32 v79, 0xffff0000, v34
	v_lshlrev_b32_e32 v80, 16, v35
	v_and_b32_e32 v81, 0xffff0000, v35
	v_lshlrev_b32_e32 v30, 16, v36
	v_lshlrev_b32_e32 v32, 16, v37
	s_waitcnt vmcnt(10)
	v_lshlrev_b32_e32 v35, 16, v46
	v_and_b32_e32 v37, 0xffff0000, v46
	v_mul_f32_e32 v34, v33, v33
	s_waitcnt vmcnt(9)
	v_lshlrev_b32_e32 v83, 16, v49
	v_lshlrev_b32_e32 v82, 16, v48
	v_and_b32_e32 v49, 0xffff0000, v49
	v_and_b32_e32 v48, 0xffff0000, v48
	s_waitcnt vmcnt(8)
	v_and_b32_e32 v85, 0xffff0000, v50
	v_mul_f32_e32 v36, v31, v31
	v_lshlrev_b32_e32 v84, 16, v50
	v_lshlrev_b32_e32 v50, 16, v51
	v_and_b32_e32 v51, 0xffff0000, v51
	s_waitcnt vmcnt(5)
	v_lshlrev_b32_e32 v90, 16, v58
	v_and_b32_e32 v91, 0xffff0000, v58
	v_lshlrev_b32_e32 v92, 16, v59
	v_and_b32_e32 v93, 0xffff0000, v59
	s_waitcnt vmcnt(3)
	v_lshlrev_b32_e32 v59, 16, v62
	v_pk_fma_f32 v[98:99], v[32:33], v[32:33], v[34:35] op_sel_hi:[1,1,0]
	v_pk_mul_f32 v[100:101], v[48:49], v[48:49]
	v_pk_fma_f32 v[102:103], v[30:31], v[30:31], v[36:37] op_sel_hi:[1,1,0]
	v_mul_f32_e32 v58, v85, v85
	s_waitcnt vmcnt(2)
	v_lshlrev_b32_e32 v106, 16, v64
	v_and_b32_e32 v107, 0xffff0000, v64
	v_lshlrev_b32_e32 v64, 16, v65
	v_and_b32_e32 v65, 0xffff0000, v65
	s_waitcnt vmcnt(1)
	v_lshlrev_b32_e32 v109, 16, v67
	v_lshlrev_b32_e32 v108, 16, v66
	v_and_b32_e32 v67, 0xffff0000, v67
	v_and_b32_e32 v66, 0xffff0000, v66
	v_lshlrev_b32_e32 v46, 16, v47
	v_and_b32_e32 v47, 0xffff0000, v47
	v_lshlrev_b32_e32 v94, 16, v60
	v_and_b32_e32 v95, 0xffff0000, v60
	v_lshlrev_b32_e32 v96, 16, v61
	v_and_b32_e32 v97, 0xffff0000, v61
	v_and_b32_e32 v61, 0xffff0000, v62
	v_mov_b32_e32 v105, v35
	v_mul_f32_e32 v60, v51, v51
	v_mov_b32_e32 v112, v82
	v_mov_b32_e32 v113, v48
	v_mov_b32_e32 v48, v83
	v_pk_fma_f32 v[82:83], v[82:83], v[82:83], v[100:101]
	v_mov_b32_e32 v34, v102
	v_mov_b32_e32 v104, v98
	v_pk_fma_f32 v[100:101], v[84:85], v[84:85], v[58:59] op_sel_hi:[1,1,0]
	v_mul_f32_e32 v58, v65, v65
	v_pk_mul_f32 v[114:115], v[66:67], v[66:67]
	v_mul_f32_e32 v116, v107, v107
	v_mov_b32_e32 v117, v59
	v_mul_f32_e32 v119, v46, v46
	v_mul_f32_e32 v121, v47, v47
	s_waitcnt vmcnt(0)
	v_lshlrev_b32_e32 v110, 16, v70
	v_and_b32_e32 v111, 0xffff0000, v70
	v_lshlrev_b32_e32 v70, 16, v71
	v_and_b32_e32 v71, 0xffff0000, v71
	v_mov_b32_e32 v36, v35
	v_pk_add_f32 v[98:99], v[102:103], v[98:99]
	v_pk_fma_f32 v[102:103], v[50:51], v[50:51], v[60:61] op_sel_hi:[1,1,0]
	v_mov_b32_e32 v122, v108
	v_mov_b32_e32 v123, v66
	v_mov_b32_e32 v66, v109
	v_pk_mul_f32 v[34:35], v[34:35], v[104:105]
	v_pk_fma_f32 v[104:105], v[64:65], v[64:65], v[58:59] op_sel_hi:[1,1,0]
	v_pk_fma_f32 v[108:109], v[108:109], v[108:109], v[114:115]
	v_pk_fma_f32 v[114:115], v[106:107], v[106:107], v[116:117] op_sel_hi:[1,1,0]
	v_lshlrev_b32_e32 v62, 16, v63
	v_and_b32_e32 v63, 0xffff0000, v63
	v_mul_f32_e32 v118, v111, v111
	v_mul_f32_e32 v120, v71, v71
	v_mov_b32_e32 v101, v119
	v_mov_b32_e32 v103, v121
	v_mov_b32_e32 v58, v114
	v_mov_b32_e32 v116, v104
	v_mul_f32_e32 v43, v37, v37
	v_mul_f32_e32 v124, v61, v61
	v_mul_f32_e32 v125, v62, v62
	v_mul_f32_e32 v126, v63, v63
	v_mov_b32_e32 v60, v59
	v_pk_add_f32 v[82:83], v[82:83], v[82:83] op_sel:[0,1] op_sel_hi:[1,0]
	v_pk_fma_f32 v[118:119], v[110:111], v[110:111], v[118:119] op_sel_hi:[1,1,0]
	v_pk_fma_f32 v[120:121], v[70:71], v[70:71], v[120:121] op_sel_hi:[1,1,0]
	v_mov_b32_e32 v99, v35
	v_pk_add_f32 v[34:35], v[100:101], v[102:103]
	v_pk_add_f32 v[100:101], v[114:115], v[104:105]
	v_pk_add_f32 v[102:103], v[108:109], v[108:109] op_sel:[0,1] op_sel_hi:[1,0]
	v_pk_mul_f32 v[58:59], v[58:59], v[116:117]
	v_mov_b32_e32 v83, v43
	v_mov_b32_e32 v119, v125
	v_mov_b32_e32 v121, v126
	v_mov_b32_e32 v103, v124
	v_mov_b32_e32 v101, v59
	v_pk_add_f32 v[82:83], v[98:99], v[82:83]
	v_pk_add_f32 v[98:99], v[118:119], v[120:121]
	v_pk_add_f32 v[58:59], v[100:101], v[102:103]
	v_pk_add_f32 v[34:35], v[82:83], v[34:35]
	v_pk_add_f32 v[58:59], v[58:59], v[98:99]
	v_mov_b32_e32 v83, v34
	v_mov_b32_e32 v82, v58
	v_mov_b32_e32 v34, v59
	v_pk_add_f32 v[34:35], v[82:83], v[34:35]
	v_lshlrev_b32_e32 v44, 16, v28
	v_and_b32_e32 v45, 0xffff0000, v28
	v_lshlrev_b32_e32 v28, 16, v29
	v_and_b32_e32 v29, 0xffff0000, v29
	v_lshlrev_b32_e32 v86, 16, v54
	v_and_b32_e32 v87, 0xffff0000, v54
	v_lshlrev_b32_e32 v54, 16, v55
	v_and_b32_e32 v55, 0xffff0000, v55
	v_lshlrev_b32_e32 v88, 16, v56
	v_and_b32_e32 v89, 0xffff0000, v56
	v_lshlrev_b32_e32 v56, 16, v57
	v_and_b32_e32 v57, 0xffff0000, v57
	s_nop 1
	v_add_f32_dpp v34, v34, v34 row_shr:1 row_mask:0xf bank_mask:0xf
	v_add_f32_dpp v35, v35, v35 row_shr:1 row_mask:0xf bank_mask:0xf
	s_nop 0
	v_add_f32_dpp v34, v34, v34 row_shr:2 row_mask:0xf bank_mask:0xf
	v_add_f32_dpp v35, v35, v35 row_shr:2 row_mask:0xf bank_mask:0xf
	s_nop 0
	v_add_f32_dpp v34, v34, v34 row_shr:4 row_mask:0xf bank_mask:0xf
	v_add_f32_dpp v35, v35, v35 row_shr:4 row_mask:0xf bank_mask:0xf
	s_nop 0
	v_add_f32_dpp v34, v34, v34 row_shr:8 row_mask:0xf bank_mask:0xf
	v_add_f32_dpp v35, v35, v35 row_shr:8 row_mask:0xf bank_mask:0xf
	s_nop 0
	v_add_f32_dpp v34, v34, v34 row_bcast:15 row_mask:0xa bank_mask:0xf
	v_add_f32_dpp v35, v35, v35 row_bcast:15 row_mask:0xa bank_mask:0xf
	s_nop 0
	v_add_f32_dpp v34, v34, v34 row_bcast:31 row_mask:0xc bank_mask:0xf
	v_add_f32_dpp v35, v35, v35 row_bcast:31 row_mask:0xc bank_mask:0xf
	s_nop 0
	s_nop 0
	v_readlane_b32 s98, v34, 63
	v_readlane_b32 s99, v35, 63
	v_mov_b32_e32 v34, s98
	v_mov_b32_e32 v35, s99
	s_nop 0
	v_pk_fma_f32 v[34:35], v[34:35], s[2:3], v[26:27] op_sel_hi:[1,0,0]
	s_nop 0
	v_mul_f32_e32 v43, 0x4b800000, v35
	v_cmp_gt_f32_e64 s[0:1], s10, v35
	v_mul_f32_e32 v58, 0x4b800000, v34
	v_cmp_gt_f32_e32 vcc, s10, v34
	v_cndmask_b32_e64 v35, v35, v43, s[0:1]
	v_rsq_f32_e32 v35, v35
	v_cndmask_b32_e32 v34, v34, v58, vcc
	v_rsq_f32_e32 v43, v34
	v_mul_f32_e32 v34, 0x45800000, v35
	v_cndmask_b32_e64 v34, v35, v34, s[0:1]
	v_mul_f32_e32 v58, 0x45800000, v43
	v_cndmask_b32_e32 v58, v43, v58, vcc
	v_pk_mul_f32 v[82:83], v[34:35], v[30:31] op_sel_hi:[0,1]
	v_pk_mul_f32 v[30:31], v[34:35], v[32:33] op_sel_hi:[0,1]
	v_pk_mul_f32 v[32:33], v[34:35], v[112:113] op_sel_hi:[0,1]
	v_pk_mul_f32 v[48:49], v[34:35], v[48:49] op_sel_hi:[0,1]
	v_pk_mul_f32 v[84:85], v[34:35], v[84:85] op_sel_hi:[0,1]
	v_pk_mul_f32 v[50:51], v[34:35], v[50:51] op_sel_hi:[0,1]
	v_pk_mul_f32 v[36:37], v[34:35], v[36:37] op_sel_hi:[0,1]
	v_pk_mul_f32 v[98:99], v[34:35], v[46:47] op_sel_hi:[0,1]
	v_pk_mul_f32 v[100:101], v[58:59], v[106:107] op_sel_hi:[0,1]
	v_pk_mul_f32 v[64:65], v[58:59], v[64:65] op_sel_hi:[0,1]
	v_pk_mul_f32 v[102:103], v[58:59], v[122:123] op_sel_hi:[0,1]
	v_pk_mul_f32 v[66:67], v[58:59], v[66:67] op_sel_hi:[0,1]
	v_pk_mul_f32 v[104:105], v[58:59], v[110:111] op_sel_hi:[0,1]
	v_pk_mul_f32 v[70:71], v[58:59], v[70:71] op_sel_hi:[0,1]
	v_pk_mul_f32 v[106:107], v[58:59], v[60:61] op_sel_hi:[0,1]
	v_pk_mul_f32 v[108:109], v[58:59], v[62:63] op_sel_hi:[0,1]
	v_pk_fma_f32 v[30:31], v[8:9], v[30:31], v[28:29]
	v_pk_fma_f32 v[28:29], v[10:11], v[82:83], v[44:45]
	v_pk_fma_f32 v[34:35], v[12:13], v[48:49], v[72:73]
	v_pk_fma_f32 v[32:33], v[14:15], v[32:33], v[52:53]
	v_pk_fma_f32 v[46:47], v[16:17], v[50:51], v[76:77]
	v_pk_fma_f32 v[44:45], v[18:19], v[84:85], v[74:75]
	v_pk_fma_f32 v[50:51], v[20:21], v[98:99], v[80:81]
	v_pk_fma_f32 v[48:49], v[22:23], v[36:37], v[78:79]
	v_pk_fma_f32 v[54:55], v[8:9], v[64:65], v[54:55]
	v_pk_fma_f32 v[52:53], v[10:11], v[100:101], v[86:87]
	v_pk_fma_f32 v[58:59], v[12:13], v[66:67], v[56:57]
	v_pk_fma_f32 v[56:57], v[14:15], v[102:103], v[88:89]
	v_pk_fma_f32 v[62:63], v[16:17], v[70:71], v[92:93]
	v_pk_fma_f32 v[60:61], v[18:19], v[104:105], v[90:91]
	v_pk_fma_f32 v[66:67], v[20:21], v[108:109], v[96:97]
	v_pk_fma_f32 v[64:65], v[22:23], v[106:107], v[94:95]
	global_store_dwordx4 v[24:25], v[28:31], off offset:-3072 nt
	global_store_dwordx4 v[24:25], v[32:35], off offset:-2048 nt
	global_store_dwordx4 v[24:25], v[44:47], off offset:-1024 nt
	global_store_dwordx4 v[24:25], v[48:51], off nt
	global_store_dwordx4 v[68:69], v[52:55], off nt
	global_store_dwordx4 v[68:69], v[56:59], off offset:1024 nt
	global_store_dwordx4 v[68:69], v[60:63], off offset:2048 nt
	global_store_dwordx4 v[68:69], v[64:67], off offset:3072 nt
	v_lshl_add_u64 v[24:25], v[24:25], 0, s[6:7]
	s_cbranch_scc1 .LBB0_1714

	.amdhsa_kernel _Z8yoco_fwd4Args
		.amdhsa_group_segment_fixed_size 0
		.amdhsa_private_segment_fixed_size 0
		.amdhsa_kernarg_size 584
		.amdhsa_user_sgpr_count 2
		.amdhsa_user_sgpr_dispatch_ptr 0
		.amdhsa_user_sgpr_queue_ptr 0
		.amdhsa_user_sgpr_kernarg_segment_ptr 1
		.amdhsa_user_sgpr_dispatch_id 0
		.amdhsa_user_sgpr_kernarg_preload_length 0
		.amdhsa_user_sgpr_kernarg_preload_offset 0
		.amdhsa_user_sgpr_private_segment_size 0
		.amdhsa_uses_dynamic_stack 0
		.amdhsa_enable_private_segment 0
		.amdhsa_system_sgpr_workgroup_id_x 1
		.amdhsa_system_sgpr_workgroup_id_y 0
		.amdhsa_system_sgpr_workgroup_id_z 0
		.amdhsa_system_sgpr_workgroup_info 0
		.amdhsa_system_vgpr_workitem_id 2
		.amdhsa_next_free_vgpr 248
		.amdhsa_next_free_sgpr 100
		.amdhsa_accum_offset 248
		.amdhsa_reserve_vcc 1
		.amdhsa_float_round_mode_32 0
		.amdhsa_float_round_mode_16_64 0
		.amdhsa_float_denorm_mode_32 3
		.amdhsa_float_denorm_mode_16_64 3
		.amdhsa_dx10_clamp 1
		.amdhsa_ieee_mode 1
		.amdhsa_fp16_overflow 0
		.amdhsa_tg_split 0
		.amdhsa_exception_fp_ieee_invalid_op 0
		.amdhsa_exception_fp_denorm_src 0
		.amdhsa_exception_fp_ieee_div_zero 0
		.amdhsa_exception_fp_ieee_overflow 0
		.amdhsa_exception_fp_ieee_underflow 0
		.amdhsa_exception_fp_ieee_inexact 0
		.amdhsa_exception_int_div_zero 0
	.end_amdhsa_kernel

amdhsa.kernels:
  - .agpr_count:     0
    .args:
      - .offset:         0
        .size:           328
        .value_kind:     by_value
      - .offset:         328
        .size:           4
        .value_kind:     hidden_block_count_x
      - .offset:         332
        .size:           4
        .value_kind:     hidden_block_count_y
      - .offset:         336
        .size:           4
        .value_kind:     hidden_block_count_z
      - .offset:         340
        .size:           2
        .value_kind:     hidden_group_size_x
      - .offset:         342
        .size:           2
        .value_kind:     hidden_group_size_y
      - .offset:         344
        .size:           2
        .value_kind:     hidden_group_size_z
      - .offset:         346
        .size:           2
        .value_kind:     hidden_remainder_x
      - .offset:         348
        .size:           2
        .value_kind:     hidden_remainder_y
      - .offset:         350
        .size:           2
        .value_kind:     hidden_remainder_z
      - .offset:         368
        .size:           8
        .value_kind:     hidden_global_offset_x
      - .offset:         376
        .size:           8
        .value_kind:     hidden_global_offset_y
      - .offset:         384
        .size:           8
        .value_kind:     hidden_global_offset_z
      - .offset:         392
        .size:           2
        .value_kind:     hidden_grid_dims
      - .offset:         416
        .size:           8
        .value_kind:     hidden_multigrid_sync_arg
      - .offset:         448
        .size:           4
        .value_kind:     hidden_dynamic_lds_size
    .group_segment_fixed_size: 0
    .kernarg_segment_align: 8
    .kernarg_segment_size: 584
    .language:       OpenCL C
    .language_version:
      - 2
      - 0
    .max_flat_workgroup_size: 512
    .name:           _Z8yoco_fwd4Args
    .private_segment_fixed_size: 0
    .sgpr_count:     106
    .sgpr_spill_count: 5
    .symbol:         _Z8yoco_fwd4Args.kd
    .uniform_work_group_size: 1
    .uses_dynamic_stack: false
    .vgpr_count:     248
    .vgpr_spill_count: 0
    .wavefront_size: 64
